# forget-gate tile: dead denormal-rescue code of __logf removed (argument is clamped to 1e-30), bit-exact
# speedup vs baseline: 1.0044x; 1.0044x over previous
.LBB0_288:
	s_andn2_b64 vcc, exec, s[34:35]
	s_cbranch_vccnz .LBB0_290
	v_mul_f32_e32 v128, 0xbfb8aa3b, v182
	v_exp_f32_e32 v128, v128
	v_mul_f32_e32 v161, 0x3fb8aa3b, v203
	v_exp_f32_e32 v161, v161
	v_add_f32_e32 v128, 1.0, v128
	v_rcp_f32_e32 v157, v128
	v_mul_f32_e32 v128, 0x3fb8aa3b, v182
	v_exp_f32_e32 v128, v128
	v_add_f32_e32 v161, 1.0, v161
	v_rcp_f32_e32 v211, v161
	v_mul_f32_e32 v161, 0x3fb8aa3b, v181
	v_add_f32_e32 v128, 1.0, v128
	v_rcp_f32_e32 v206, v128
	v_mul_f32_e32 v128, 0xbfb8aa3b, v183
	v_exp_f32_e32 v128, v128
	v_exp_f32_e32 v161, v161
	v_add_f32_e32 v128, 1.0, v128
	v_rcp_f32_e32 v159, v128
	v_mul_f32_e32 v128, 0x3fb8aa3b, v183
	v_exp_f32_e32 v128, v128
	v_add_f32_e32 v161, 1.0, v161
	v_rcp_f32_e32 v215, v161
	v_add_f32_e32 v128, 1.0, v128
	v_rcp_f32_e32 v207, v128
	global_load_dwordx4 v[128:131], v[148:149], off offset:16
	global_load_dwordx4 v[132:135], v[148:149], off
	s_waitcnt vmcnt(1)
	v_pk_add_f32 v[222:223], v[128:129], 1.0 op_sel_hi:[1,0] neg_lo:[1,0] neg_hi:[1,0]
	s_waitcnt vmcnt(0)
	v_pk_add_f32 v[208:209], v[132:133], 1.0 op_sel_hi:[1,0] neg_lo:[1,0] neg_hi:[1,0]
	v_pk_add_f32 v[212:213], v[134:135], 1.0 op_sel_hi:[1,0] neg_lo:[1,0] neg_hi:[1,0]
	v_fma_f32 v132, v157, v208, v132
	v_max_f32_e32 v132, 0xda24260, v132
	v_fma_f32 v133, v159, v209, v133
	v_max_f32_e32 v133, 0xda24260, v133
	v_log_f32_e32 v132, v132
	v_mul_f32_e32 v159, 0x3fb8aa3b, v202
	v_exp_f32_e32 v159, v159
	v_pk_add_f32 v[230:231], v[130:131], 1.0 op_sel_hi:[1,0] neg_lo:[1,0] neg_hi:[1,0]
	v_mul_f32_e32 v157, 0x3f317217, v132
	v_fma_f32 v157, v132, s95, -v157
	v_fmac_f32_e32 v157, 0x3377d1cf, v132
	v_fmac_f32_e32 v157, 0x3f317217, v132
	v_cmp_lt_f32_e64 s[42:43], |v132|, s62
	v_add_f32_e32 v159, 1.0, v159
	v_rcp_f32_e32 v210, v159
	v_cndmask_b32_e64 v132, v132, v157, s[42:43]
	v_mul_f32_e32 v159, 0xbfb8aa3b, v203
	v_log_f32_e32 v133, v133
	v_exp_f32_e32 v159, v159
	v_pk_mul_f32 v[208:209], v[206:207], v[208:209]
	v_pk_mul_f32 v[206:207], v[210:211], v[212:213]
	v_mul_f32_e32 v157, 0x3f317217, v133
	v_fma_f32 v157, v133, s95, -v157
	v_fmac_f32_e32 v157, 0x3377d1cf, v133
	v_fmac_f32_e32 v157, 0x3f317217, v133
	v_cmp_lt_f32_e64 s[42:43], |v133|, s62
	v_add_f32_e32 v159, 1.0, v159
	v_rcp_f32_e32 v159, v159
	v_cndmask_b32_e64 v133, v133, v157, s[42:43]
	v_mul_f32_e32 v157, 0xbfb8aa3b, v202
	v_exp_f32_e32 v157, v157
	v_fmac_f32_e32 v135, v159, v213
	v_max_f32_e32 v135, 0xda24260, v135
	v_mul_f32_e32 v159, 0x3fb8aa3b, v180
	v_add_f32_e32 v157, 1.0, v157
	v_rcp_f32_e32 v157, v157
	v_exp_f32_e32 v159, v159
	v_lshl_add_u64 v[210:211], v[146:147], 0, v[178:179]
	v_fma_f32 v134, v157, v212, v134
	v_max_f32_e32 v134, 0xda24260, v134
	v_add_f32_e32 v159, 1.0, v159
	v_rcp_f32_e32 v214, v159
	v_log_f32_e32 v134, v134
	v_mul_f32_e32 v159, 0xbfb8aa3b, v181
	v_exp_f32_e32 v159, v159
	v_mul_f32_e32 v157, 0x3f317217, v134
	v_fma_f32 v157, v134, s95, -v157
	v_fmac_f32_e32 v157, 0x3377d1cf, v134
	v_fmac_f32_e32 v157, 0x3f317217, v134
	v_cmp_lt_f32_e64 s[42:43], |v134|, s62
	v_add_f32_e32 v159, 1.0, v159
	v_rcp_f32_e32 v159, v159
	v_cndmask_b32_e64 v134, v134, v157, s[42:43]
	s_nop 0
	v_log_f32_e32 v135, v135
	s_nop 0
	v_mul_f32_e32 v157, 0x3f317217, v135
	v_fma_f32 v157, v135, s95, -v157
	v_fmac_f32_e32 v157, 0x3377d1cf, v135
	v_fmac_f32_e32 v157, 0x3f317217, v135
	v_cmp_lt_f32_e64 s[42:43], |v135|, s62
	s_nop 1
	v_cndmask_b32_e64 v135, v135, v157, s[42:43]
	v_mul_f32_e32 v157, 0xbfb8aa3b, v180
	v_exp_f32_e32 v157, v157
	s_nop 0
	v_add_f32_e32 v157, 1.0, v157
	v_rcp_f32_e32 v157, v157
	s_nop 0
	v_fma_f32 v128, v157, v222, v128
	v_max_f32_e32 v128, 0xda24260, v128
	v_cmp_gt_f32_e32 vcc, s93, v128
	s_nop 1
	v_cndmask_b32_e64 v157, 0, 32, vcc
	v_ldexp_f32 v128, v128, v157
	v_log_f32_e32 v128, v128
	s_nop 0
	v_mul_f32_e32 v157, 0x3f317217, v128
	v_fma_f32 v157, v128, s95, -v157
	v_fmac_f32_e32 v157, 0x3377d1cf, v128
	v_fmac_f32_e32 v157, 0x3f317217, v128
	v_cmp_lt_f32_e64 s[42:43], |v128|, s62
	s_nop 1
	v_cndmask_b32_e64 v128, v128, v157, s[42:43]
	v_cndmask_b32_e32 v157, 0, v225, vcc
	v_sub_f32_e32 v218, v128, v157
	v_fma_f32 v128, v159, v223, v129
	v_max_f32_e32 v128, 0xda24260, v128
	v_cmp_gt_f32_e32 vcc, s93, v128
	s_nop 1
	v_cndmask_b32_e64 v129, 0, 32, vcc
	v_ldexp_f32 v128, v128, v129
	v_log_f32_e32 v128, v128
	s_nop 0
	v_mul_f32_e32 v129, 0x3f317217, v128
	v_fma_f32 v129, v128, s95, -v129
	v_fmac_f32_e32 v129, 0x3377d1cf, v128
	v_fmac_f32_e32 v129, 0x3f317217, v128
	v_cmp_lt_f32_e64 s[42:43], |v128|, s62
	s_nop 1
	v_cndmask_b32_e64 v128, v128, v129, s[42:43]
	v_cndmask_b32_e32 v129, 0, v225, vcc
	v_sub_f32_e32 v219, v128, v129
	v_mul_f32_e32 v128, 0xbfb8aa3b, v204
	v_exp_f32_e32 v128, v128
	v_mul_f32_e32 v129, 0xbfb8aa3b, v205
	v_exp_f32_e32 v129, v129
	v_add_f32_e32 v128, 1.0, v128
	v_rcp_f32_e32 v157, v128
	v_add_f32_e32 v129, 1.0, v129
	v_rcp_f32_e32 v159, v129
	v_mul_f32_e32 v128, 0x3fb8aa3b, v204
	v_fma_f32 v130, v157, v230, v130
	v_max_f32_e32 v130, 0xda24260, v130
	v_cmp_gt_f32_e32 vcc, s93, v130
	v_fmac_f32_e32 v131, v159, v231
	v_mul_f32_e32 v129, 0x3fb8aa3b, v205
	v_cndmask_b32_e64 v157, 0, 32, vcc
	v_ldexp_f32 v130, v130, v157
	v_log_f32_e32 v130, v130
	v_exp_f32_e32 v128, v128
	v_exp_f32_e32 v129, v129
	v_mul_f32_e32 v157, 0x3f317217, v130
	v_fma_f32 v157, v130, s95, -v157
	v_fmac_f32_e32 v157, 0x3377d1cf, v130
	v_fmac_f32_e32 v157, 0x3f317217, v130
	v_cmp_lt_f32_e64 s[42:43], |v130|, s62
	v_add_f32_e32 v128, 1.0, v128
	v_add_f32_e32 v129, 1.0, v129
	v_cndmask_b32_e64 v130, v130, v157, s[42:43]
	v_cndmask_b32_e32 v157, 0, v225, vcc
	v_sub_f32_e32 v220, v130, v157
	v_max_f32_e32 v130, 0xda24260, v131
	v_cmp_gt_f32_e32 vcc, s93, v130
	v_rcp_f32_e32 v128, v128
	v_rcp_f32_e32 v129, v129
	v_cndmask_b32_e64 v131, 0, 32, vcc
	v_ldexp_f32 v130, v130, v131
	v_log_f32_e32 v130, v130
	v_pk_mul_f32 v[128:129], v[128:129], v[230:231]
	v_mul_f32_e32 v131, 0x3f317217, v130
	v_fma_f32 v131, v130, s95, -v131
	v_fmac_f32_e32 v131, 0x3377d1cf, v130
	v_fmac_f32_e32 v131, 0x3f317217, v130
	v_cmp_lt_f32_e64 s[42:43], |v130|, s62
	s_nop 1
	v_cndmask_b32_e64 v130, v130, v131, s[42:43]
	v_cndmask_b32_e32 v131, 0, v225, vcc
	v_sub_f32_e32 v221, v130, v131
	v_pk_mul_f32 v[130:131], v[214:215], v[222:223]
	global_store_dwordx4 v[210:211], v[132:135], off
	global_store_dwordx4 v[210:211], v[218:221], off offset:16

.LBB0_300:
	s_andn2_b64 vcc, exec, s[36:37]
	s_cbranch_vccnz .LBB0_302
	global_load_dwordx4 v[120:123], v[148:149], off offset:528
	global_load_dwordx4 v[124:127], v[148:149], off offset:512
	v_mul_f32_e32 v157, 0xbfb8aa3b, v132
	v_exp_f32_e32 v157, v157
	v_mul_f32_e32 v159, 0x3fb8aa3b, v132
	v_exp_f32_e32 v159, v159
	v_mul_f32_e32 v161, 0x3fb8aa3b, v133
	v_add_f32_e32 v157, 1.0, v157
	v_rcp_f32_e32 v157, v157
	v_add_f32_e32 v159, 1.0, v159
	v_rcp_f32_e32 v182, v159
	v_mul_f32_e32 v159, 0xbfb8aa3b, v133
	v_exp_f32_e32 v159, v159
	v_exp_f32_e32 v161, v161
	v_lshl_add_u64 v[178:179], v[150:151], 0, v[178:179]
	v_add_f32_e32 v159, 1.0, v159
	v_rcp_f32_e32 v159, v159
	v_add_f32_e32 v161, 1.0, v161
	v_rcp_f32_e32 v183, v161
	v_mul_f32_e32 v161, 0x3fb8aa3b, v135
	v_exp_f32_e32 v161, v161
	s_waitcnt vmcnt(1)
	v_pk_add_f32 v[214:215], v[120:121], 1.0 op_sel_hi:[1,0] neg_lo:[1,0] neg_hi:[1,0]
	s_waitcnt vmcnt(0)
	v_pk_add_f32 v[202:203], v[124:125], 1.0 op_sel_hi:[1,0] neg_lo:[1,0] neg_hi:[1,0]
	v_pk_add_f32 v[206:207], v[126:127], 1.0 op_sel_hi:[1,0] neg_lo:[1,0] neg_hi:[1,0]
	v_fma_f32 v124, v157, v202, v124
	v_max_f32_e32 v124, 0xda24260, v124
	v_fma_f32 v125, v159, v203, v125
	v_max_f32_e32 v125, 0xda24260, v125
	v_log_f32_e32 v124, v124
	v_mul_f32_e32 v159, 0x3fb8aa3b, v134
	v_exp_f32_e32 v159, v159
	v_pk_add_f32 v[218:219], v[122:123], 1.0 op_sel_hi:[1,0] neg_lo:[1,0] neg_hi:[1,0]
	v_mul_f32_e32 v157, 0x3f317217, v124
	v_fma_f32 v157, v124, s95, -v157
	v_fmac_f32_e32 v157, 0x3377d1cf, v124
	v_fmac_f32_e32 v157, 0x3f317217, v124
	v_cmp_lt_f32_e64 s[46:47], |v124|, s62
	v_add_f32_e32 v159, 1.0, v159
	v_rcp_f32_e32 v204, v159
	v_cndmask_b32_e64 v124, v124, v157, s[46:47]
	v_mul_f32_e32 v159, 0xbfb8aa3b, v135
	v_log_f32_e32 v125, v125
	v_exp_f32_e32 v159, v159
	v_add_f32_e32 v161, 1.0, v161
	v_rcp_f32_e32 v205, v161
	v_mul_f32_e32 v157, 0x3f317217, v125
	v_fma_f32 v157, v125, s95, -v157
	v_fmac_f32_e32 v157, 0x3377d1cf, v125
	v_fmac_f32_e32 v157, 0x3f317217, v125
	v_cmp_lt_f32_e64 s[46:47], |v125|, s62
	v_add_f32_e32 v159, 1.0, v159
	v_rcp_f32_e32 v159, v159
	v_cndmask_b32_e64 v125, v125, v157, s[46:47]
	v_mul_f32_e32 v157, 0xbfb8aa3b, v134
	v_exp_f32_e32 v157, v157
	v_fmac_f32_e32 v127, v159, v207
	v_max_f32_e32 v127, 0xda24260, v127
	v_mul_f32_e32 v159, 0x3fb8aa3b, v130
	v_add_f32_e32 v157, 1.0, v157
	v_rcp_f32_e32 v157, v157
	v_exp_f32_e32 v159, v159
	v_mul_f32_e32 v161, 0x3fb8aa3b, v131
	v_exp_f32_e32 v161, v161
	v_fma_f32 v126, v157, v206, v126
	v_max_f32_e32 v126, 0xda24260, v126
	v_add_f32_e32 v159, 1.0, v159
	v_rcp_f32_e32 v208, v159
	v_log_f32_e32 v126, v126
	v_mul_f32_e32 v159, 0xbfb8aa3b, v131
	v_exp_f32_e32 v159, v159
	v_add_f32_e32 v161, 1.0, v161
	v_mul_f32_e32 v157, 0x3f317217, v126
	v_fma_f32 v157, v126, s95, -v157
	v_fmac_f32_e32 v157, 0x3377d1cf, v126
	v_fmac_f32_e32 v157, 0x3f317217, v126
	v_cmp_lt_f32_e64 s[46:47], |v126|, s62
	v_add_f32_e32 v159, 1.0, v159
	v_rcp_f32_e32 v159, v159
	v_cndmask_b32_e64 v126, v126, v157, s[46:47]
	v_rcp_f32_e32 v209, v161
	v_log_f32_e32 v127, v127
	v_pk_mul_f32 v[202:203], v[182:183], v[202:203]
	v_pk_mul_f32 v[182:183], v[204:205], v[206:207]
	v_mul_f32_e32 v157, 0x3f317217, v127
	v_fma_f32 v157, v127, s95, -v157
	v_fmac_f32_e32 v157, 0x3377d1cf, v127
	v_fmac_f32_e32 v157, 0x3f317217, v127
	v_cmp_lt_f32_e64 s[46:47], |v127|, s62
	s_nop 1
	v_cndmask_b32_e64 v127, v127, v157, s[46:47]
	v_mul_f32_e32 v157, 0xbfb8aa3b, v130
	v_exp_f32_e32 v157, v157
	s_nop 0
	v_add_f32_e32 v157, 1.0, v157
	v_rcp_f32_e32 v157, v157
	s_nop 0
	v_fma_f32 v120, v157, v214, v120
	v_max_f32_e32 v120, 0xda24260, v120
	v_cmp_gt_f32_e32 vcc, s93, v120
	s_nop 1
	v_cndmask_b32_e64 v157, 0, 32, vcc
	v_ldexp_f32 v120, v120, v157
	v_log_f32_e32 v120, v120
	s_nop 0
	v_mul_f32_e32 v157, 0x3f317217, v120
	v_fma_f32 v157, v120, s95, -v157
	v_fmac_f32_e32 v157, 0x3377d1cf, v120
	v_fmac_f32_e32 v157, 0x3f317217, v120
	v_cmp_lt_f32_e64 s[46:47], |v120|, s62
	s_nop 1
	v_cndmask_b32_e64 v120, v120, v157, s[46:47]
	v_cndmask_b32_e32 v157, 0, v225, vcc
	v_sub_f32_e32 v210, v120, v157
	v_fma_f32 v120, v159, v215, v121
	v_max_f32_e32 v120, 0xda24260, v120
	v_cmp_gt_f32_e32 vcc, s93, v120
	s_nop 1
	v_cndmask_b32_e64 v121, 0, 32, vcc
	v_ldexp_f32 v120, v120, v121
	v_log_f32_e32 v120, v120
	s_nop 0
	v_mul_f32_e32 v121, 0x3f317217, v120
	v_fma_f32 v121, v120, s95, -v121
	v_fmac_f32_e32 v121, 0x3377d1cf, v120
	v_fmac_f32_e32 v121, 0x3f317217, v120
	v_cmp_lt_f32_e64 s[46:47], |v120|, s62
	s_nop 1
	v_cndmask_b32_e64 v120, v120, v121, s[46:47]
	v_cndmask_b32_e32 v121, 0, v225, vcc
	v_sub_f32_e32 v211, v120, v121
	v_mul_f32_e32 v120, 0xbfb8aa3b, v180
	v_exp_f32_e32 v120, v120
	v_mul_f32_e32 v121, 0xbfb8aa3b, v181
	v_exp_f32_e32 v121, v121
	v_add_f32_e32 v120, 1.0, v120
	v_rcp_f32_e32 v157, v120
	v_add_f32_e32 v121, 1.0, v121
	v_rcp_f32_e32 v159, v121
	v_mul_f32_e32 v120, 0x3fb8aa3b, v180
	v_fma_f32 v122, v157, v218, v122
	v_max_f32_e32 v122, 0xda24260, v122
	v_cmp_gt_f32_e32 vcc, s93, v122
	v_fmac_f32_e32 v123, v159, v219
	v_mul_f32_e32 v121, 0x3fb8aa3b, v181
	v_cndmask_b32_e64 v157, 0, 32, vcc
	v_ldexp_f32 v122, v122, v157
	v_log_f32_e32 v122, v122
	v_exp_f32_e32 v120, v120
	v_exp_f32_e32 v121, v121
	v_mul_f32_e32 v157, 0x3f317217, v122
	v_fma_f32 v157, v122, s95, -v157
	v_fmac_f32_e32 v157, 0x3377d1cf, v122
	v_fmac_f32_e32 v157, 0x3f317217, v122
	v_cmp_lt_f32_e64 s[46:47], |v122|, s62
	v_add_f32_e32 v120, 1.0, v120
	v_add_f32_e32 v121, 1.0, v121
	v_cndmask_b32_e64 v122, v122, v157, s[46:47]
	v_cndmask_b32_e32 v157, 0, v225, vcc
	v_sub_f32_e32 v212, v122, v157
	v_max_f32_e32 v122, 0xda24260, v123
	v_cmp_gt_f32_e32 vcc, s93, v122
	v_rcp_f32_e32 v120, v120
	v_rcp_f32_e32 v121, v121
	v_cndmask_b32_e64 v123, 0, 32, vcc
	v_ldexp_f32 v122, v122, v123
	v_log_f32_e32 v122, v122
	v_pk_mul_f32 v[120:121], v[120:121], v[218:219]
	v_mul_f32_e32 v123, 0x3f317217, v122
	v_fma_f32 v123, v122, s95, -v123
	v_fmac_f32_e32 v123, 0x3377d1cf, v122
	v_fmac_f32_e32 v123, 0x3f317217, v122
	v_cmp_lt_f32_e64 s[46:47], |v122|, s62
	s_nop 1
	v_cndmask_b32_e64 v122, v122, v123, s[46:47]
	v_cndmask_b32_e32 v123, 0, v225, vcc
	v_sub_f32_e32 v213, v122, v123
	v_pk_mul_f32 v[122:123], v[208:209], v[214:215]
	global_store_dwordx4 v[178:179], v[124:127], off
	global_store_dwordx4 v[178:179], v[210:213], off offset:16

.LBB0_312:
	s_andn2_b64 vcc, exec, s[36:37]
	s_cbranch_vccnz .LBB0_314
	v_mul_f32_e32 v120, 0xbfb8aa3b, v134
	v_exp_f32_e32 v120, v120
	v_mul_f32_e32 v159, 0x3fb8aa3b, v179
	v_exp_f32_e32 v159, v159
	v_add_f32_e32 v120, 1.0, v120
	v_rcp_f32_e32 v131, v120
	v_mul_f32_e32 v120, 0x3fb8aa3b, v134
	v_exp_f32_e32 v120, v120
	v_add_f32_e32 v159, 1.0, v159
	v_rcp_f32_e32 v205, v159
	v_mul_f32_e32 v159, 0x3fb8aa3b, v133
	v_add_f32_e32 v120, 1.0, v120
	v_rcp_f32_e32 v182, v120
	v_mul_f32_e32 v120, 0xbfb8aa3b, v135
	v_exp_f32_e32 v120, v120
	v_exp_f32_e32 v159, v159
	v_add_f32_e32 v120, 1.0, v120
	v_rcp_f32_e32 v157, v120
	v_mul_f32_e32 v120, 0x3fb8aa3b, v135
	v_exp_f32_e32 v120, v120
	v_add_f32_e32 v159, 1.0, v159
	v_rcp_f32_e32 v209, v159
	v_add_f32_e32 v120, 1.0, v120
	v_rcp_f32_e32 v183, v120
	global_load_dwordx4 v[120:123], v[148:149], off offset:16
	global_load_dwordx4 v[124:127], v[148:149], off
	s_waitcnt vmcnt(1)
	v_pk_add_f32 v[214:215], v[120:121], 1.0 op_sel_hi:[1,0] neg_lo:[1,0] neg_hi:[1,0]
	s_waitcnt vmcnt(0)
	v_pk_add_f32 v[202:203], v[124:125], 1.0 op_sel_hi:[1,0] neg_lo:[1,0] neg_hi:[1,0]
	v_pk_add_f32 v[206:207], v[126:127], 1.0 op_sel_hi:[1,0] neg_lo:[1,0] neg_hi:[1,0]
	v_fma_f32 v124, v131, v202, v124
	v_max_f32_e32 v124, 0xda24260, v124
	v_fma_f32 v125, v157, v203, v125
	v_max_f32_e32 v125, 0xda24260, v125
	v_log_f32_e32 v124, v124
	v_mul_f32_e32 v157, 0x3fb8aa3b, v178
	v_exp_f32_e32 v157, v157
	v_pk_add_f32 v[218:219], v[122:123], 1.0 op_sel_hi:[1,0] neg_lo:[1,0] neg_hi:[1,0]
	v_mul_f32_e32 v131, 0x3f317217, v124
	v_fma_f32 v131, v124, s95, -v131
	v_fmac_f32_e32 v131, 0x3377d1cf, v124
	v_fmac_f32_e32 v131, 0x3f317217, v124
	v_cmp_lt_f32_e64 s[46:47], |v124|, s62
	v_add_f32_e32 v157, 1.0, v157
	v_rcp_f32_e32 v204, v157
	v_cndmask_b32_e64 v124, v124, v131, s[46:47]
	v_mul_f32_e32 v157, 0xbfb8aa3b, v179
	v_log_f32_e32 v125, v125
	v_exp_f32_e32 v157, v157
	v_pk_mul_f32 v[202:203], v[182:183], v[202:203]
	v_pk_mul_f32 v[182:183], v[204:205], v[206:207]
	v_mul_f32_e32 v131, 0x3f317217, v125
	v_fma_f32 v131, v125, s95, -v131
	v_fmac_f32_e32 v131, 0x3377d1cf, v125
	v_fmac_f32_e32 v131, 0x3f317217, v125
	v_cmp_lt_f32_e64 s[46:47], |v125|, s62
	v_add_f32_e32 v157, 1.0, v157
	v_rcp_f32_e32 v157, v157
	v_cndmask_b32_e64 v125, v125, v131, s[46:47]
	v_mul_f32_e32 v131, 0xbfb8aa3b, v178
	v_exp_f32_e32 v131, v131
	v_fmac_f32_e32 v127, v157, v207
	v_max_f32_e32 v127, 0xda24260, v127
	v_mul_f32_e32 v157, 0x3fb8aa3b, v132
	v_add_f32_e32 v131, 1.0, v131
	v_rcp_f32_e32 v131, v131
	v_exp_f32_e32 v157, v157
	v_lshl_add_u64 v[204:205], v[146:147], 0, v[128:129]
	v_fma_f32 v126, v131, v206, v126
	v_max_f32_e32 v126, 0xda24260, v126
	v_add_f32_e32 v157, 1.0, v157
	v_rcp_f32_e32 v208, v157
	v_log_f32_e32 v126, v126
	v_mul_f32_e32 v157, 0xbfb8aa3b, v133
	v_exp_f32_e32 v157, v157
	v_mul_f32_e32 v131, 0x3f317217, v126
	v_fma_f32 v131, v126, s95, -v131
	v_fmac_f32_e32 v131, 0x3377d1cf, v126
	v_fmac_f32_e32 v131, 0x3f317217, v126
	v_cmp_lt_f32_e64 s[46:47], |v126|, s62
	v_add_f32_e32 v157, 1.0, v157
	v_rcp_f32_e32 v157, v157
	v_cndmask_b32_e64 v126, v126, v131, s[46:47]
	s_nop 0
	v_log_f32_e32 v127, v127
	s_nop 0
	v_mul_f32_e32 v131, 0x3f317217, v127
	v_fma_f32 v131, v127, s95, -v131
	v_fmac_f32_e32 v131, 0x3377d1cf, v127
	v_fmac_f32_e32 v131, 0x3f317217, v127
	v_cmp_lt_f32_e64 s[46:47], |v127|, s62
	s_nop 1
	v_cndmask_b32_e64 v127, v127, v131, s[46:47]
	v_mul_f32_e32 v131, 0xbfb8aa3b, v132
	v_exp_f32_e32 v131, v131
	s_nop 0
	v_add_f32_e32 v131, 1.0, v131
	v_rcp_f32_e32 v131, v131
	s_nop 0
	v_fma_f32 v120, v131, v214, v120
	v_max_f32_e32 v120, 0xda24260, v120
	v_cmp_gt_f32_e32 vcc, s93, v120
	s_nop 1
	v_cndmask_b32_e64 v131, 0, 32, vcc
	v_ldexp_f32 v120, v120, v131
	v_log_f32_e32 v120, v120
	s_nop 0
	v_mul_f32_e32 v131, 0x3f317217, v120
	v_fma_f32 v131, v120, s95, -v131
	v_fmac_f32_e32 v131, 0x3377d1cf, v120
	v_fmac_f32_e32 v131, 0x3f317217, v120
	v_cmp_lt_f32_e64 s[46:47], |v120|, s62
	s_nop 1
	v_cndmask_b32_e64 v120, v120, v131, s[46:47]
	v_cndmask_b32_e32 v131, 0, v225, vcc
	v_sub_f32_e32 v210, v120, v131
	v_fma_f32 v120, v157, v215, v121
	v_max_f32_e32 v120, 0xda24260, v120
	v_cmp_gt_f32_e32 vcc, s93, v120
	s_nop 1
	v_cndmask_b32_e64 v121, 0, 32, vcc
	v_ldexp_f32 v120, v120, v121
	v_log_f32_e32 v120, v120
	s_nop 0
	v_mul_f32_e32 v121, 0x3f317217, v120
	v_fma_f32 v121, v120, s95, -v121
	v_fmac_f32_e32 v121, 0x3377d1cf, v120
	v_fmac_f32_e32 v121, 0x3f317217, v120
	v_cmp_lt_f32_e64 s[46:47], |v120|, s62
	s_nop 1
	v_cndmask_b32_e64 v120, v120, v121, s[46:47]
	v_cndmask_b32_e32 v121, 0, v225, vcc
	v_sub_f32_e32 v211, v120, v121
	v_mul_f32_e32 v120, 0xbfb8aa3b, v180
	v_exp_f32_e32 v120, v120
	v_mul_f32_e32 v121, 0xbfb8aa3b, v181
	v_exp_f32_e32 v121, v121
	v_add_f32_e32 v120, 1.0, v120
	v_rcp_f32_e32 v131, v120
	v_add_f32_e32 v121, 1.0, v121
	v_rcp_f32_e32 v157, v121
	v_mul_f32_e32 v120, 0x3fb8aa3b, v180
	v_fma_f32 v122, v131, v218, v122
	v_max_f32_e32 v122, 0xda24260, v122
	v_cmp_gt_f32_e32 vcc, s93, v122
	v_fmac_f32_e32 v123, v157, v219
	v_mul_f32_e32 v121, 0x3fb8aa3b, v181
	v_cndmask_b32_e64 v131, 0, 32, vcc
	v_ldexp_f32 v122, v122, v131
	v_log_f32_e32 v122, v122
	v_exp_f32_e32 v120, v120
	v_exp_f32_e32 v121, v121
	v_mul_f32_e32 v131, 0x3f317217, v122
	v_fma_f32 v131, v122, s95, -v131
	v_fmac_f32_e32 v131, 0x3377d1cf, v122
	v_fmac_f32_e32 v131, 0x3f317217, v122
	v_cmp_lt_f32_e64 s[46:47], |v122|, s62
	v_add_f32_e32 v120, 1.0, v120
	v_add_f32_e32 v121, 1.0, v121
	v_cndmask_b32_e64 v122, v122, v131, s[46:47]
	v_cndmask_b32_e32 v131, 0, v225, vcc
	v_sub_f32_e32 v212, v122, v131
	v_max_f32_e32 v122, 0xda24260, v123
	v_cmp_gt_f32_e32 vcc, s93, v122
	v_rcp_f32_e32 v120, v120
	v_rcp_f32_e32 v121, v121
	v_cndmask_b32_e64 v123, 0, 32, vcc
	v_ldexp_f32 v122, v122, v123
	v_log_f32_e32 v122, v122
	v_pk_mul_f32 v[120:121], v[120:121], v[218:219]
	v_mul_f32_e32 v123, 0x3f317217, v122
	v_fma_f32 v123, v122, s95, -v123
	v_fmac_f32_e32 v123, 0x3377d1cf, v122
	v_fmac_f32_e32 v123, 0x3f317217, v122
	v_cmp_lt_f32_e64 s[46:47], |v122|, s62
	s_nop 1
	v_cndmask_b32_e64 v122, v122, v123, s[46:47]
	v_cndmask_b32_e32 v123, 0, v225, vcc
	v_sub_f32_e32 v213, v122, v123
	v_pk_mul_f32 v[122:123], v[208:209], v[214:215]
	global_store_dwordx4 v[204:205], v[124:127], off
	global_store_dwordx4 v[204:205], v[210:213], off offset:16

.LBB0_324:
	s_andn2_b64 vcc, exec, s[36:37]
	s_cbranch_vccnz .LBB0_326
	global_load_dwordx4 v[112:115], v[148:149], off offset:528
	global_load_dwordx4 v[116:119], v[148:149], off offset:512
	v_mul_f32_e32 v132, 0xbfb8aa3b, v124
	v_exp_f32_e32 v132, v132
	v_mul_f32_e32 v133, 0xbfb8aa3b, v125
	v_exp_f32_e32 v133, v133
	v_mul_f32_e32 v161, 0x3fb8aa3b, v127
	v_add_f32_e32 v132, 1.0, v132
	v_rcp_f32_e32 v157, v132
	v_add_f32_e32 v133, 1.0, v133
	v_rcp_f32_e32 v159, v133
	v_exp_f32_e32 v161, v161
	v_mul_f32_e32 v132, 0x3fb8aa3b, v124
	v_mul_f32_e32 v133, 0x3fb8aa3b, v125
	v_exp_f32_e32 v132, v132
	v_add_f32_e32 v161, 1.0, v161
	v_rcp_f32_e32 v179, v161
	v_mul_f32_e32 v161, 0x3fb8aa3b, v123
	v_exp_f32_e32 v133, v133
	v_exp_f32_e32 v161, v161
	v_add_f32_e32 v132, 1.0, v132
	v_rcp_f32_e32 v132, v132
	v_add_f32_e32 v133, 1.0, v133
	v_add_f32_e32 v161, 1.0, v161
	v_rcp_f32_e32 v133, v133
	v_rcp_f32_e32 v183, v161
	v_lshl_add_u64 v[128:129], v[150:151], 0, v[128:129]
	s_waitcnt vmcnt(1)
	v_pk_add_f32 v[206:207], v[112:113], 1.0 op_sel_hi:[1,0] neg_lo:[1,0] neg_hi:[1,0]
	s_waitcnt vmcnt(0)
	v_pk_add_f32 v[134:135], v[116:117], 1.0 op_sel_hi:[1,0] neg_lo:[1,0] neg_hi:[1,0]
	v_pk_add_f32 v[180:181], v[118:119], 1.0 op_sel_hi:[1,0] neg_lo:[1,0] neg_hi:[1,0]
	v_fma_f32 v116, v157, v134, v116
	v_max_f32_e32 v116, 0xda24260, v116
	v_fma_f32 v117, v159, v135, v117
	v_max_f32_e32 v117, 0xda24260, v117
	v_log_f32_e32 v116, v116
	v_mul_f32_e32 v159, 0x3fb8aa3b, v126
	v_exp_f32_e32 v159, v159
	v_pk_add_f32 v[208:209], v[114:115], 1.0 op_sel_hi:[1,0] neg_lo:[1,0] neg_hi:[1,0]
	v_mul_f32_e32 v157, 0x3f317217, v116
	v_fma_f32 v157, v116, s95, -v157
	v_fmac_f32_e32 v157, 0x3377d1cf, v116
	v_fmac_f32_e32 v157, 0x3f317217, v116
	v_cmp_lt_f32_e64 s[46:47], |v116|, s62
	v_add_f32_e32 v159, 1.0, v159
	v_rcp_f32_e32 v178, v159
	v_cndmask_b32_e64 v116, v116, v157, s[46:47]
	v_mul_f32_e32 v159, 0xbfb8aa3b, v127
	v_log_f32_e32 v117, v117
	v_exp_f32_e32 v159, v159
	v_pk_mul_f32 v[134:135], v[132:133], v[134:135]
	v_pk_mul_f32 v[132:133], v[178:179], v[180:181]
	v_mul_f32_e32 v157, 0x3f317217, v117
	v_fma_f32 v157, v117, s95, -v157
	v_fmac_f32_e32 v157, 0x3377d1cf, v117
	v_fmac_f32_e32 v157, 0x3f317217, v117
	v_cmp_lt_f32_e64 s[46:47], |v117|, s62
	v_add_f32_e32 v159, 1.0, v159
	v_rcp_f32_e32 v159, v159
	v_cndmask_b32_e64 v117, v117, v157, s[46:47]
	v_mul_f32_e32 v157, 0xbfb8aa3b, v126
	v_exp_f32_e32 v157, v157
	v_fmac_f32_e32 v119, v159, v181
	v_max_f32_e32 v119, 0xda24260, v119
	v_mul_f32_e32 v159, 0x3fb8aa3b, v122
	v_add_f32_e32 v157, 1.0, v157
	v_rcp_f32_e32 v157, v157
	v_exp_f32_e32 v159, v159
	v_fma_f32 v118, v157, v180, v118
	v_max_f32_e32 v118, 0xda24260, v118
	v_add_f32_e32 v159, 1.0, v159
	v_rcp_f32_e32 v182, v159
	v_log_f32_e32 v118, v118
	v_mul_f32_e32 v159, 0xbfb8aa3b, v123
	v_exp_f32_e32 v159, v159
	v_mul_f32_e32 v157, 0x3f317217, v118
	v_fma_f32 v157, v118, s95, -v157
	v_fmac_f32_e32 v157, 0x3377d1cf, v118
	v_fmac_f32_e32 v157, 0x3f317217, v118
	v_cmp_lt_f32_e64 s[46:47], |v118|, s62
	v_add_f32_e32 v159, 1.0, v159
	v_rcp_f32_e32 v159, v159
	v_cndmask_b32_e64 v118, v118, v157, s[46:47]
	s_nop 0
	v_log_f32_e32 v119, v119
	s_nop 0
	v_mul_f32_e32 v157, 0x3f317217, v119
	v_fma_f32 v157, v119, s95, -v157
	v_fmac_f32_e32 v157, 0x3377d1cf, v119
	v_fmac_f32_e32 v157, 0x3f317217, v119
	v_cmp_lt_f32_e64 s[46:47], |v119|, s62
	s_nop 1
	v_cndmask_b32_e64 v119, v119, v157, s[46:47]
	v_mul_f32_e32 v157, 0xbfb8aa3b, v122
	v_exp_f32_e32 v157, v157
	s_nop 0
	v_add_f32_e32 v157, 1.0, v157
	v_rcp_f32_e32 v157, v157
	s_nop 0
	v_fma_f32 v112, v157, v206, v112
	v_max_f32_e32 v112, 0xda24260, v112
	v_cmp_gt_f32_e32 vcc, s93, v112
	s_nop 1
	v_cndmask_b32_e64 v157, 0, 32, vcc
	v_ldexp_f32 v112, v112, v157
	v_log_f32_e32 v112, v112
	s_nop 0
	v_mul_f32_e32 v157, 0x3f317217, v112
	v_fma_f32 v157, v112, s95, -v157
	v_fmac_f32_e32 v157, 0x3377d1cf, v112
	v_fmac_f32_e32 v157, 0x3f317217, v112
	v_cmp_lt_f32_e64 s[46:47], |v112|, s62
	s_nop 1
	v_cndmask_b32_e64 v112, v112, v157, s[46:47]
	v_cndmask_b32_e32 v157, 0, v225, vcc
	v_sub_f32_e32 v202, v112, v157
	v_fma_f32 v112, v159, v207, v113
	v_max_f32_e32 v112, 0xda24260, v112
	v_cmp_gt_f32_e32 vcc, s93, v112
	s_nop 1
	v_cndmask_b32_e64 v113, 0, 32, vcc
	v_ldexp_f32 v112, v112, v113
	v_log_f32_e32 v112, v112
	s_nop 0
	v_mul_f32_e32 v113, 0x3f317217, v112
	v_fma_f32 v113, v112, s95, -v113
	v_fmac_f32_e32 v113, 0x3377d1cf, v112
	v_fmac_f32_e32 v113, 0x3f317217, v112
	v_cmp_lt_f32_e64 s[46:47], |v112|, s62
	s_nop 1
	v_cndmask_b32_e64 v112, v112, v113, s[46:47]
	v_cndmask_b32_e32 v113, 0, v225, vcc
	v_sub_f32_e32 v203, v112, v113
	v_mul_f32_e32 v112, 0xbfb8aa3b, v130
	v_exp_f32_e32 v112, v112
	v_mul_f32_e32 v113, 0xbfb8aa3b, v131
	v_exp_f32_e32 v113, v113
	v_add_f32_e32 v112, 1.0, v112
	v_rcp_f32_e32 v157, v112
	v_add_f32_e32 v113, 1.0, v113
	v_rcp_f32_e32 v159, v113
	v_mul_f32_e32 v112, 0x3fb8aa3b, v130
	v_fma_f32 v114, v157, v208, v114
	v_max_f32_e32 v114, 0xda24260, v114
	v_cmp_gt_f32_e32 vcc, s93, v114
	v_fmac_f32_e32 v115, v159, v209
	v_mul_f32_e32 v113, 0x3fb8aa3b, v131
	v_cndmask_b32_e64 v157, 0, 32, vcc
	v_ldexp_f32 v114, v114, v157
	v_log_f32_e32 v114, v114
	v_exp_f32_e32 v112, v112
	v_exp_f32_e32 v113, v113
	v_mul_f32_e32 v157, 0x3f317217, v114
	v_fma_f32 v157, v114, s95, -v157
	v_fmac_f32_e32 v157, 0x3377d1cf, v114
	v_fmac_f32_e32 v157, 0x3f317217, v114
	v_cmp_lt_f32_e64 s[46:47], |v114|, s62
	v_add_f32_e32 v112, 1.0, v112
	v_add_f32_e32 v113, 1.0, v113
	v_cndmask_b32_e64 v114, v114, v157, s[46:47]
	v_cndmask_b32_e32 v157, 0, v225, vcc
	v_sub_f32_e32 v204, v114, v157
	v_max_f32_e32 v114, 0xda24260, v115
	v_cmp_gt_f32_e32 vcc, s93, v114
	v_rcp_f32_e32 v112, v112
	v_rcp_f32_e32 v113, v113
	v_cndmask_b32_e64 v115, 0, 32, vcc
	v_ldexp_f32 v114, v114, v115
	v_log_f32_e32 v114, v114
	v_pk_mul_f32 v[112:113], v[112:113], v[208:209]
	v_mul_f32_e32 v115, 0x3f317217, v114
	v_fma_f32 v115, v114, s95, -v115
	v_fmac_f32_e32 v115, 0x3377d1cf, v114
	v_fmac_f32_e32 v115, 0x3f317217, v114
	v_cmp_lt_f32_e64 s[46:47], |v114|, s62
	s_nop 1
	v_cndmask_b32_e64 v114, v114, v115, s[46:47]
	v_cndmask_b32_e32 v115, 0, v225, vcc
	v_sub_f32_e32 v205, v114, v115
	v_pk_mul_f32 v[114:115], v[182:183], v[206:207]
	global_store_dwordx4 v[128:129], v[116:119], off
	global_store_dwordx4 v[128:129], v[202:205], off offset:16

.LBB0_336:
	s_andn2_b64 vcc, exec, s[36:37]
	s_cbranch_vccnz .LBB0_338
	v_mul_f32_e32 v112, 0xbfb8aa3b, v126
	v_exp_f32_e32 v112, v112
	v_mul_f32_e32 v159, 0x3fb8aa3b, v129
	v_exp_f32_e32 v159, v159
	v_add_f32_e32 v112, 1.0, v112
	v_rcp_f32_e32 v123, v112
	v_mul_f32_e32 v112, 0x3fb8aa3b, v126
	v_exp_f32_e32 v112, v112
	v_add_f32_e32 v159, 1.0, v159
	v_rcp_f32_e32 v179, v159
	v_mul_f32_e32 v159, 0x3fb8aa3b, v125
	v_add_f32_e32 v112, 1.0, v112
	v_rcp_f32_e32 v132, v112
	v_mul_f32_e32 v112, 0xbfb8aa3b, v127
	v_exp_f32_e32 v112, v112
	v_exp_f32_e32 v159, v159
	v_add_f32_e32 v112, 1.0, v112
	v_rcp_f32_e32 v157, v112
	v_mul_f32_e32 v112, 0x3fb8aa3b, v127
	v_exp_f32_e32 v112, v112
	v_add_f32_e32 v159, 1.0, v159
	v_rcp_f32_e32 v183, v159
	v_add_f32_e32 v112, 1.0, v112
	v_rcp_f32_e32 v133, v112
	global_load_dwordx4 v[112:115], v[148:149], off offset:16
	global_load_dwordx4 v[116:119], v[148:149], off
	s_waitcnt vmcnt(1)
	v_pk_add_f32 v[206:207], v[112:113], 1.0 op_sel_hi:[1,0] neg_lo:[1,0] neg_hi:[1,0]
	s_waitcnt vmcnt(0)
	v_pk_add_f32 v[134:135], v[116:117], 1.0 op_sel_hi:[1,0] neg_lo:[1,0] neg_hi:[1,0]
	v_pk_add_f32 v[180:181], v[118:119], 1.0 op_sel_hi:[1,0] neg_lo:[1,0] neg_hi:[1,0]
	v_fma_f32 v116, v123, v134, v116
	v_max_f32_e32 v116, 0xda24260, v116
	v_fma_f32 v117, v157, v135, v117
	v_max_f32_e32 v117, 0xda24260, v117
	v_log_f32_e32 v116, v116
	v_mul_f32_e32 v157, 0x3fb8aa3b, v128
	v_exp_f32_e32 v157, v157
	v_pk_add_f32 v[208:209], v[114:115], 1.0 op_sel_hi:[1,0] neg_lo:[1,0] neg_hi:[1,0]
	v_mul_f32_e32 v123, 0x3f317217, v116
	v_fma_f32 v123, v116, s95, -v123
	v_fmac_f32_e32 v123, 0x3377d1cf, v116
	v_fmac_f32_e32 v123, 0x3f317217, v116
	v_cmp_lt_f32_e64 s[46:47], |v116|, s62
	v_add_f32_e32 v157, 1.0, v157
	v_rcp_f32_e32 v178, v157
	v_cndmask_b32_e64 v116, v116, v123, s[46:47]
	v_mul_f32_e32 v157, 0xbfb8aa3b, v129
	v_log_f32_e32 v117, v117
	v_exp_f32_e32 v157, v157
	v_pk_mul_f32 v[134:135], v[132:133], v[134:135]
	v_pk_mul_f32 v[132:133], v[178:179], v[180:181]
	v_mul_f32_e32 v123, 0x3f317217, v117
	v_fma_f32 v123, v117, s95, -v123
	v_fmac_f32_e32 v123, 0x3377d1cf, v117
	v_fmac_f32_e32 v123, 0x3f317217, v117
	v_cmp_lt_f32_e64 s[46:47], |v117|, s62
	v_add_f32_e32 v157, 1.0, v157
	v_rcp_f32_e32 v157, v157
	v_cndmask_b32_e64 v117, v117, v123, s[46:47]
	v_mul_f32_e32 v123, 0xbfb8aa3b, v128
	v_exp_f32_e32 v123, v123
	v_fmac_f32_e32 v119, v157, v181
	v_max_f32_e32 v119, 0xda24260, v119
	v_mul_f32_e32 v157, 0x3fb8aa3b, v124
	v_add_f32_e32 v123, 1.0, v123
	v_rcp_f32_e32 v123, v123
	v_exp_f32_e32 v157, v157
	v_lshl_add_u64 v[178:179], v[146:147], 0, v[120:121]
	v_fma_f32 v118, v123, v180, v118
	v_max_f32_e32 v118, 0xda24260, v118
	v_add_f32_e32 v157, 1.0, v157
	v_rcp_f32_e32 v182, v157
	v_log_f32_e32 v118, v118
	v_mul_f32_e32 v157, 0xbfb8aa3b, v125
	v_exp_f32_e32 v157, v157
	v_mul_f32_e32 v123, 0x3f317217, v118
	v_fma_f32 v123, v118, s95, -v123
	v_fmac_f32_e32 v123, 0x3377d1cf, v118
	v_fmac_f32_e32 v123, 0x3f317217, v118
	v_cmp_lt_f32_e64 s[46:47], |v118|, s62
	v_add_f32_e32 v157, 1.0, v157
	v_rcp_f32_e32 v157, v157
	v_cndmask_b32_e64 v118, v118, v123, s[46:47]
	s_nop 0
	v_log_f32_e32 v119, v119
	s_nop 0
	v_mul_f32_e32 v123, 0x3f317217, v119
	v_fma_f32 v123, v119, s95, -v123
	v_fmac_f32_e32 v123, 0x3377d1cf, v119
	v_fmac_f32_e32 v123, 0x3f317217, v119
	v_cmp_lt_f32_e64 s[46:47], |v119|, s62
	s_nop 1
	v_cndmask_b32_e64 v119, v119, v123, s[46:47]
	v_mul_f32_e32 v123, 0xbfb8aa3b, v124
	v_exp_f32_e32 v123, v123
	s_nop 0
	v_add_f32_e32 v123, 1.0, v123
	v_rcp_f32_e32 v123, v123
	s_nop 0
	v_fma_f32 v112, v123, v206, v112
	v_max_f32_e32 v112, 0xda24260, v112
	v_cmp_gt_f32_e32 vcc, s93, v112
	s_nop 1
	v_cndmask_b32_e64 v123, 0, 32, vcc
	v_ldexp_f32 v112, v112, v123
	v_log_f32_e32 v112, v112
	s_nop 0
	v_mul_f32_e32 v123, 0x3f317217, v112
	v_fma_f32 v123, v112, s95, -v123
	v_fmac_f32_e32 v123, 0x3377d1cf, v112
	v_fmac_f32_e32 v123, 0x3f317217, v112
	v_cmp_lt_f32_e64 s[46:47], |v112|, s62
	s_nop 1
	v_cndmask_b32_e64 v112, v112, v123, s[46:47]
	v_cndmask_b32_e32 v123, 0, v225, vcc
	v_sub_f32_e32 v202, v112, v123
	v_fma_f32 v112, v157, v207, v113
	v_max_f32_e32 v112, 0xda24260, v112
	v_cmp_gt_f32_e32 vcc, s93, v112
	s_nop 1
	v_cndmask_b32_e64 v113, 0, 32, vcc
	v_ldexp_f32 v112, v112, v113
	v_log_f32_e32 v112, v112
	s_nop 0
	v_mul_f32_e32 v113, 0x3f317217, v112
	v_fma_f32 v113, v112, s95, -v113
	v_fmac_f32_e32 v113, 0x3377d1cf, v112
	v_fmac_f32_e32 v113, 0x3f317217, v112
	v_cmp_lt_f32_e64 s[46:47], |v112|, s62
	s_nop 1
	v_cndmask_b32_e64 v112, v112, v113, s[46:47]
	v_cndmask_b32_e32 v113, 0, v225, vcc
	v_sub_f32_e32 v203, v112, v113
	v_mul_f32_e32 v112, 0xbfb8aa3b, v130
	v_exp_f32_e32 v112, v112
	v_mul_f32_e32 v113, 0xbfb8aa3b, v131
	v_exp_f32_e32 v113, v113
	v_add_f32_e32 v112, 1.0, v112
	v_rcp_f32_e32 v123, v112
	v_add_f32_e32 v113, 1.0, v113
	v_rcp_f32_e32 v157, v113
	v_mul_f32_e32 v112, 0x3fb8aa3b, v130
	v_fma_f32 v114, v123, v208, v114
	v_max_f32_e32 v114, 0xda24260, v114
	v_cmp_gt_f32_e32 vcc, s93, v114
	v_fmac_f32_e32 v115, v157, v209
	v_mul_f32_e32 v113, 0x3fb8aa3b, v131
	v_cndmask_b32_e64 v123, 0, 32, vcc
	v_ldexp_f32 v114, v114, v123
	v_log_f32_e32 v114, v114
	v_exp_f32_e32 v112, v112
	v_exp_f32_e32 v113, v113
	v_mul_f32_e32 v123, 0x3f317217, v114
	v_fma_f32 v123, v114, s95, -v123
	v_fmac_f32_e32 v123, 0x3377d1cf, v114
	v_fmac_f32_e32 v123, 0x3f317217, v114
	v_cmp_lt_f32_e64 s[46:47], |v114|, s62
	v_add_f32_e32 v112, 1.0, v112
	v_add_f32_e32 v113, 1.0, v113
	v_cndmask_b32_e64 v114, v114, v123, s[46:47]
	v_cndmask_b32_e32 v123, 0, v225, vcc
	v_sub_f32_e32 v204, v114, v123
	v_max_f32_e32 v114, 0xda24260, v115
	v_cmp_gt_f32_e32 vcc, s93, v114
	v_rcp_f32_e32 v112, v112
	v_rcp_f32_e32 v113, v113
	v_cndmask_b32_e64 v115, 0, 32, vcc
	v_ldexp_f32 v114, v114, v115
	v_log_f32_e32 v114, v114
	v_pk_mul_f32 v[112:113], v[112:113], v[208:209]
	v_mul_f32_e32 v115, 0x3f317217, v114
	v_fma_f32 v115, v114, s95, -v115
	v_fmac_f32_e32 v115, 0x3377d1cf, v114
	v_fmac_f32_e32 v115, 0x3f317217, v114
	v_cmp_lt_f32_e64 s[46:47], |v114|, s62
	s_nop 1
	v_cndmask_b32_e64 v114, v114, v115, s[46:47]
	v_cndmask_b32_e32 v115, 0, v225, vcc
	v_sub_f32_e32 v205, v114, v115
	v_pk_mul_f32 v[114:115], v[182:183], v[206:207]
	global_store_dwordx4 v[178:179], v[116:119], off
	global_store_dwordx4 v[178:179], v[202:205], off offset:16

.LBB0_348:
	s_andn2_b64 vcc, exec, s[36:37]
	s_cbranch_vccnz .LBB0_350
	global_load_dwordx4 v[104:107], v[148:149], off offset:528
	global_load_dwordx4 v[108:111], v[148:149], off offset:512
	v_mul_f32_e32 v124, 0xbfb8aa3b, v116
	v_exp_f32_e32 v124, v124
	v_mul_f32_e32 v125, 0xbfb8aa3b, v117
	v_exp_f32_e32 v125, v125
	v_lshl_add_u64 v[120:121], v[150:151], 0, v[120:121]
	v_add_f32_e32 v124, 1.0, v124
	v_rcp_f32_e32 v128, v124
	v_add_f32_e32 v125, 1.0, v125
	v_rcp_f32_e32 v129, v125
	v_mul_f32_e32 v124, 0x3fb8aa3b, v116
	v_mul_f32_e32 v125, 0x3fb8aa3b, v117
	v_exp_f32_e32 v124, v124
	v_exp_f32_e32 v125, v125
	v_add_f32_e32 v124, 1.0, v124
	v_add_f32_e32 v125, 1.0, v125
	v_rcp_f32_e32 v124, v124
	v_rcp_f32_e32 v125, v125
	s_waitcnt vmcnt(1)
	v_pk_add_f32 v[134:135], v[104:105], 1.0 op_sel_hi:[1,0] neg_lo:[1,0] neg_hi:[1,0]
	s_waitcnt vmcnt(0)
	v_pk_add_f32 v[126:127], v[108:109], 1.0 op_sel_hi:[1,0] neg_lo:[1,0] neg_hi:[1,0]
	v_pk_add_f32 v[130:131], v[110:111], 1.0 op_sel_hi:[1,0] neg_lo:[1,0] neg_hi:[1,0]
	v_fma_f32 v108, v128, v126, v108
	v_max_f32_e32 v108, 0xda24260, v108
	v_fma_f32 v109, v129, v127, v109
	v_max_f32_e32 v109, 0xda24260, v109
	v_log_f32_e32 v108, v108
	v_mul_f32_e32 v129, 0xbfb8aa3b, v119
	v_exp_f32_e32 v129, v129
	v_pk_add_f32 v[182:183], v[106:107], 1.0 op_sel_hi:[1,0] neg_lo:[1,0] neg_hi:[1,0]
	v_mul_f32_e32 v128, 0x3f317217, v108
	v_fma_f32 v128, v108, s95, -v128
	v_fmac_f32_e32 v128, 0x3377d1cf, v108
	v_fmac_f32_e32 v128, 0x3f317217, v108
	v_cmp_lt_f32_e64 s[46:47], |v108|, s62
	v_add_f32_e32 v129, 1.0, v129
	v_rcp_f32_e32 v133, v129
	v_cndmask_b32_e64 v108, v108, v128, s[46:47]
	v_fmac_f32_e32 v111, v133, v131
	v_log_f32_e32 v109, v109
	v_max_f32_e32 v111, 0xda24260, v111
	v_mul_f32_e32 v133, 0xbfb8aa3b, v115
	v_exp_f32_e32 v133, v133
	v_mul_f32_e32 v128, 0x3f317217, v109
	v_fma_f32 v128, v109, s95, -v128
	v_fmac_f32_e32 v128, 0x3377d1cf, v109
	v_fmac_f32_e32 v128, 0x3f317217, v109
	v_cmp_lt_f32_e64 s[46:47], |v109|, s62
	v_add_f32_e32 v133, 1.0, v133
	v_rcp_f32_e32 v159, v133
	v_cndmask_b32_e64 v109, v109, v128, s[46:47]
	v_mul_f32_e32 v128, 0xbfb8aa3b, v118
	v_exp_f32_e32 v128, v128
	v_mul_f32_e32 v129, 0x3fb8aa3b, v119
	v_mul_f32_e32 v133, 0x3fb8aa3b, v115
	v_exp_f32_e32 v129, v129
	v_add_f32_e32 v128, 1.0, v128
	v_rcp_f32_e32 v132, v128
	v_mul_f32_e32 v128, 0x3fb8aa3b, v118
	v_exp_f32_e32 v128, v128
	v_exp_f32_e32 v133, v133
	v_fma_f32 v110, v132, v130, v110
	v_max_f32_e32 v110, 0xda24260, v110
	v_add_f32_e32 v128, 1.0, v128
	v_add_f32_e32 v129, 1.0, v129
	v_log_f32_e32 v110, v110
	v_add_f32_e32 v133, 1.0, v133
	v_rcp_f32_e32 v128, v128
	v_rcp_f32_e32 v129, v129
	v_mul_f32_e32 v132, 0x3f317217, v110
	v_fma_f32 v132, v110, s95, -v132
	v_fmac_f32_e32 v132, 0x3377d1cf, v110
	v_fmac_f32_e32 v132, 0x3f317217, v110
	v_cmp_lt_f32_e64 s[46:47], |v110|, s62
	v_rcp_f32_e32 v133, v133
	v_pk_mul_f32 v[126:127], v[124:125], v[126:127]
	v_cndmask_b32_e64 v110, v110, v132, s[46:47]
	v_pk_mul_f32 v[124:125], v[128:129], v[130:131]
	v_log_f32_e32 v111, v111
	s_nop 0
	v_mul_f32_e32 v132, 0x3f317217, v111
	v_fma_f32 v132, v111, s95, -v132
	v_fmac_f32_e32 v132, 0x3377d1cf, v111
	v_fmac_f32_e32 v132, 0x3f317217, v111
	v_cmp_lt_f32_e64 s[46:47], |v111|, s62
	s_nop 1
	v_cndmask_b32_e64 v111, v111, v132, s[46:47]
	v_mul_f32_e32 v132, 0xbfb8aa3b, v114
	v_exp_f32_e32 v132, v132
	s_nop 0
	v_add_f32_e32 v132, 1.0, v132
	v_rcp_f32_e32 v157, v132
	v_mul_f32_e32 v132, 0x3fb8aa3b, v114
	v_exp_f32_e32 v132, v132
	v_fma_f32 v104, v157, v134, v104
	v_max_f32_e32 v104, 0xda24260, v104
	v_cmp_gt_f32_e32 vcc, s93, v104
	v_add_f32_e32 v132, 1.0, v132
	v_rcp_f32_e32 v132, v132
	v_cndmask_b32_e64 v157, 0, 32, vcc
	v_ldexp_f32 v104, v104, v157
	v_log_f32_e32 v104, v104
	s_nop 0
	v_mul_f32_e32 v157, 0x3f317217, v104
	v_fma_f32 v157, v104, s95, -v157
	v_fmac_f32_e32 v157, 0x3377d1cf, v104
	v_fmac_f32_e32 v157, 0x3f317217, v104
	v_cmp_lt_f32_e64 s[46:47], |v104|, s62
	s_nop 1
	v_cndmask_b32_e64 v104, v104, v157, s[46:47]
	v_cndmask_b32_e32 v157, 0, v225, vcc
	v_sub_f32_e32 v178, v104, v157
	v_fma_f32 v104, v159, v135, v105
	v_max_f32_e32 v104, 0xda24260, v104
	v_cmp_gt_f32_e32 vcc, s93, v104
	s_nop 1
	v_cndmask_b32_e64 v105, 0, 32, vcc
	v_ldexp_f32 v104, v104, v105
	v_log_f32_e32 v104, v104
	s_nop 0
	v_mul_f32_e32 v105, 0x3f317217, v104
	v_fma_f32 v105, v104, s95, -v105
	v_fmac_f32_e32 v105, 0x3377d1cf, v104
	v_fmac_f32_e32 v105, 0x3f317217, v104
	v_cmp_lt_f32_e64 s[46:47], |v104|, s62
	s_nop 1
	v_cndmask_b32_e64 v104, v104, v105, s[46:47]
	v_cndmask_b32_e32 v105, 0, v225, vcc
	v_sub_f32_e32 v179, v104, v105
	v_mul_f32_e32 v104, 0xbfb8aa3b, v122
	v_exp_f32_e32 v104, v104
	v_mul_f32_e32 v105, 0xbfb8aa3b, v123
	v_exp_f32_e32 v105, v105
	v_add_f32_e32 v104, 1.0, v104
	v_rcp_f32_e32 v157, v104
	v_add_f32_e32 v105, 1.0, v105
	v_rcp_f32_e32 v159, v105
	v_mul_f32_e32 v104, 0x3fb8aa3b, v122
	v_fma_f32 v106, v157, v182, v106
	v_max_f32_e32 v106, 0xda24260, v106
	v_cmp_gt_f32_e32 vcc, s93, v106
	v_fmac_f32_e32 v107, v159, v183
	v_mul_f32_e32 v105, 0x3fb8aa3b, v123
	v_cndmask_b32_e64 v157, 0, 32, vcc
	v_ldexp_f32 v106, v106, v157
	v_log_f32_e32 v106, v106
	v_exp_f32_e32 v104, v104
	v_exp_f32_e32 v105, v105
	v_mul_f32_e32 v157, 0x3f317217, v106
	v_fma_f32 v157, v106, s95, -v157
	v_fmac_f32_e32 v157, 0x3377d1cf, v106
	v_fmac_f32_e32 v157, 0x3f317217, v106
	v_cmp_lt_f32_e64 s[46:47], |v106|, s62
	v_add_f32_e32 v104, 1.0, v104
	v_add_f32_e32 v105, 1.0, v105
	v_cndmask_b32_e64 v106, v106, v157, s[46:47]
	v_cndmask_b32_e32 v157, 0, v225, vcc
	v_sub_f32_e32 v180, v106, v157
	v_max_f32_e32 v106, 0xda24260, v107
	v_cmp_gt_f32_e32 vcc, s93, v106
	v_rcp_f32_e32 v104, v104
	v_rcp_f32_e32 v105, v105
	v_cndmask_b32_e64 v107, 0, 32, vcc
	v_ldexp_f32 v106, v106, v107
	v_log_f32_e32 v106, v106
	v_pk_mul_f32 v[104:105], v[104:105], v[182:183]
	v_mul_f32_e32 v107, 0x3f317217, v106
	v_fma_f32 v107, v106, s95, -v107
	v_fmac_f32_e32 v107, 0x3377d1cf, v106
	v_fmac_f32_e32 v107, 0x3f317217, v106
	v_cmp_lt_f32_e64 s[46:47], |v106|, s62
	s_nop 1
	v_cndmask_b32_e64 v106, v106, v107, s[46:47]
	v_cndmask_b32_e32 v107, 0, v225, vcc
	v_sub_f32_e32 v181, v106, v107
	v_pk_mul_f32 v[106:107], v[132:133], v[134:135]
	global_store_dwordx4 v[120:121], v[108:111], off
	global_store_dwordx4 v[120:121], v[178:181], off offset:16

.LBB0_360:
	s_andn2_b64 vcc, exec, s[36:37]
	s_cbranch_vccnz .LBB0_362
	v_mul_f32_e32 v104, 0xbfb8aa3b, v118
	v_exp_f32_e32 v104, v104
	v_mul_f32_e32 v129, 0xbfb8aa3b, v121
	v_exp_f32_e32 v129, v129
	v_mul_f32_e32 v133, 0xbfb8aa3b, v117
	v_add_f32_e32 v104, 1.0, v104
	v_rcp_f32_e32 v115, v104
	v_mul_f32_e32 v104, 0x3fb8aa3b, v118
	v_exp_f32_e32 v104, v104
	v_add_f32_e32 v129, 1.0, v129
	v_rcp_f32_e32 v132, v129
	v_exp_f32_e32 v133, v133
	v_add_f32_e32 v104, 1.0, v104
	v_rcp_f32_e32 v124, v104
	v_mul_f32_e32 v104, 0xbfb8aa3b, v119
	v_exp_f32_e32 v104, v104
	v_add_f32_e32 v133, 1.0, v133
	v_rcp_f32_e32 v157, v133
	v_mul_f32_e32 v129, 0x3fb8aa3b, v121
	v_add_f32_e32 v104, 1.0, v104
	v_rcp_f32_e32 v128, v104
	v_mul_f32_e32 v104, 0x3fb8aa3b, v119
	v_exp_f32_e32 v104, v104
	v_mul_f32_e32 v133, 0x3fb8aa3b, v117
	v_exp_f32_e32 v129, v129
	v_exp_f32_e32 v133, v133
	v_add_f32_e32 v104, 1.0, v104
	v_rcp_f32_e32 v125, v104
	global_load_dwordx4 v[104:107], v[148:149], off offset:16
	global_load_dwordx4 v[108:111], v[148:149], off
	v_add_f32_e32 v129, 1.0, v129
	v_add_f32_e32 v133, 1.0, v133
	v_rcp_f32_e32 v129, v129
	v_rcp_f32_e32 v133, v133
	s_waitcnt vmcnt(1)
	v_pk_add_f32 v[134:135], v[104:105], 1.0 op_sel_hi:[1,0] neg_lo:[1,0] neg_hi:[1,0]
	s_waitcnt vmcnt(0)
	v_pk_add_f32 v[126:127], v[108:109], 1.0 op_sel_hi:[1,0] neg_lo:[1,0] neg_hi:[1,0]
	v_pk_add_f32 v[130:131], v[110:111], 1.0 op_sel_hi:[1,0] neg_lo:[1,0] neg_hi:[1,0]
	v_fma_f32 v108, v115, v126, v108
	v_max_f32_e32 v108, 0xda24260, v108
	v_fma_f32 v109, v128, v127, v109
	v_max_f32_e32 v109, 0xda24260, v109
	v_log_f32_e32 v108, v108
	v_fmac_f32_e32 v111, v132, v131
	v_max_f32_e32 v111, 0xda24260, v111
	v_pk_add_f32 v[182:183], v[106:107], 1.0 op_sel_hi:[1,0] neg_lo:[1,0] neg_hi:[1,0]
	v_mul_f32_e32 v115, 0x3f317217, v108
	v_fma_f32 v115, v108, s95, -v115
	v_fmac_f32_e32 v115, 0x3377d1cf, v108
	v_fmac_f32_e32 v115, 0x3f317217, v108
	v_cmp_lt_f32_e64 s[46:47], |v108|, s62
	v_mul_f32_e32 v128, 0x3fb8aa3b, v120
	v_mul_f32_e32 v132, 0x3fb8aa3b, v116
	v_cndmask_b32_e64 v108, v108, v115, s[46:47]
	v_exp_f32_e32 v128, v128
	v_log_f32_e32 v109, v109
	v_exp_f32_e32 v132, v132
	v_add_f32_e32 v128, 1.0, v128
	v_rcp_f32_e32 v128, v128
	v_mul_f32_e32 v115, 0x3f317217, v109
	v_fma_f32 v115, v109, s95, -v115
	v_fmac_f32_e32 v115, 0x3377d1cf, v109
	v_fmac_f32_e32 v115, 0x3f317217, v109
	v_cmp_lt_f32_e64 s[46:47], |v109|, s62
	v_add_f32_e32 v132, 1.0, v132
	v_rcp_f32_e32 v132, v132
	v_cndmask_b32_e64 v109, v109, v115, s[46:47]
	v_mul_f32_e32 v115, 0xbfb8aa3b, v120
	v_exp_f32_e32 v115, v115
	v_pk_mul_f32 v[126:127], v[124:125], v[126:127]
	v_pk_mul_f32 v[124:125], v[128:129], v[130:131]
	v_lshl_add_u64 v[128:129], v[146:147], 0, v[112:113]
	v_add_f32_e32 v115, 1.0, v115
	v_rcp_f32_e32 v115, v115
	s_nop 0
	v_fma_f32 v110, v115, v130, v110
	v_max_f32_e32 v110, 0xda24260, v110
	s_nop 1
	v_log_f32_e32 v110, v110
	s_nop 0
	v_mul_f32_e32 v115, 0x3f317217, v110
	v_fma_f32 v115, v110, s95, -v115
	v_fmac_f32_e32 v115, 0x3377d1cf, v110
	v_fmac_f32_e32 v115, 0x3f317217, v110
	v_cmp_lt_f32_e64 s[46:47], |v110|, s62
	s_nop 1
	v_cndmask_b32_e64 v110, v110, v115, s[46:47]
	s_nop 0
	v_log_f32_e32 v111, v111
	s_nop 0
	v_mul_f32_e32 v115, 0x3f317217, v111
	v_fma_f32 v115, v111, s95, -v115
	v_fmac_f32_e32 v115, 0x3377d1cf, v111
	v_fmac_f32_e32 v115, 0x3f317217, v111
	v_cmp_lt_f32_e64 s[46:47], |v111|, s62
	s_nop 1
	v_cndmask_b32_e64 v111, v111, v115, s[46:47]
	v_mul_f32_e32 v115, 0xbfb8aa3b, v116
	v_exp_f32_e32 v115, v115
	s_nop 0
	v_add_f32_e32 v115, 1.0, v115
	v_rcp_f32_e32 v115, v115
	s_nop 0
	v_fma_f32 v104, v115, v134, v104
	v_max_f32_e32 v104, 0xda24260, v104
	v_cmp_gt_f32_e32 vcc, s93, v104
	s_nop 1
	v_cndmask_b32_e64 v115, 0, 32, vcc
	v_ldexp_f32 v104, v104, v115
	v_log_f32_e32 v104, v104
	s_nop 0
	v_mul_f32_e32 v115, 0x3f317217, v104
	v_fma_f32 v115, v104, s95, -v115
	v_fmac_f32_e32 v115, 0x3377d1cf, v104
	v_fmac_f32_e32 v115, 0x3f317217, v104
	v_cmp_lt_f32_e64 s[46:47], |v104|, s62
	s_nop 1
	v_cndmask_b32_e64 v104, v104, v115, s[46:47]
	v_cndmask_b32_e32 v115, 0, v225, vcc
	v_sub_f32_e32 v178, v104, v115
	v_fma_f32 v104, v157, v135, v105
	v_max_f32_e32 v104, 0xda24260, v104
	v_cmp_gt_f32_e32 vcc, s93, v104
	s_nop 1
	v_cndmask_b32_e64 v105, 0, 32, vcc
	v_ldexp_f32 v104, v104, v105
	v_log_f32_e32 v104, v104
	s_nop 0
	v_mul_f32_e32 v105, 0x3f317217, v104
	v_fma_f32 v105, v104, s95, -v105
	v_fmac_f32_e32 v105, 0x3377d1cf, v104
	v_fmac_f32_e32 v105, 0x3f317217, v104
	v_cmp_lt_f32_e64 s[46:47], |v104|, s62
	s_nop 1
	v_cndmask_b32_e64 v104, v104, v105, s[46:47]
	v_cndmask_b32_e32 v105, 0, v225, vcc
	v_sub_f32_e32 v179, v104, v105
	v_mul_f32_e32 v104, 0xbfb8aa3b, v122
	v_exp_f32_e32 v104, v104
	v_mul_f32_e32 v105, 0xbfb8aa3b, v123
	v_exp_f32_e32 v105, v105
	v_add_f32_e32 v104, 1.0, v104
	v_rcp_f32_e32 v115, v104
	v_add_f32_e32 v105, 1.0, v105
	v_rcp_f32_e32 v157, v105
	v_mul_f32_e32 v104, 0x3fb8aa3b, v122
	v_fma_f32 v106, v115, v182, v106
	v_max_f32_e32 v106, 0xda24260, v106
	v_cmp_gt_f32_e32 vcc, s93, v106
	v_fmac_f32_e32 v107, v157, v183
	v_mul_f32_e32 v105, 0x3fb8aa3b, v123
	v_cndmask_b32_e64 v115, 0, 32, vcc
	v_ldexp_f32 v106, v106, v115
	v_log_f32_e32 v106, v106
	v_exp_f32_e32 v104, v104
	v_exp_f32_e32 v105, v105
	v_mul_f32_e32 v115, 0x3f317217, v106
	v_fma_f32 v115, v106, s95, -v115
	v_fmac_f32_e32 v115, 0x3377d1cf, v106
	v_fmac_f32_e32 v115, 0x3f317217, v106
	v_cmp_lt_f32_e64 s[46:47], |v106|, s62
	v_add_f32_e32 v104, 1.0, v104
	v_add_f32_e32 v105, 1.0, v105
	v_cndmask_b32_e64 v106, v106, v115, s[46:47]
	v_cndmask_b32_e32 v115, 0, v225, vcc
	v_sub_f32_e32 v180, v106, v115
	v_max_f32_e32 v106, 0xda24260, v107
	v_cmp_gt_f32_e32 vcc, s93, v106
	v_rcp_f32_e32 v104, v104
	v_rcp_f32_e32 v105, v105
	v_cndmask_b32_e64 v107, 0, 32, vcc
	v_ldexp_f32 v106, v106, v107
	v_log_f32_e32 v106, v106
	v_pk_mul_f32 v[104:105], v[104:105], v[182:183]
	v_mul_f32_e32 v107, 0x3f317217, v106
	v_fma_f32 v107, v106, s95, -v107
	v_fmac_f32_e32 v107, 0x3377d1cf, v106
	v_fmac_f32_e32 v107, 0x3f317217, v106
	v_cmp_lt_f32_e64 s[46:47], |v106|, s62
	s_nop 1
	v_cndmask_b32_e64 v106, v106, v107, s[46:47]
	v_cndmask_b32_e32 v107, 0, v225, vcc
	v_sub_f32_e32 v181, v106, v107
	v_pk_mul_f32 v[106:107], v[132:133], v[134:135]
	global_store_dwordx4 v[128:129], v[108:111], off
	global_store_dwordx4 v[128:129], v[178:181], off offset:16

.LBB0_372:
	s_andn2_b64 vcc, exec, s[36:37]
	s_cbranch_vccnz .LBB0_374
	global_load_dwordx4 v[96:99], v[148:149], off offset:528
	global_load_dwordx4 v[100:103], v[148:149], off offset:512
	v_mul_f32_e32 v116, 0xbfb8aa3b, v108
	v_exp_f32_e32 v116, v116
	v_mul_f32_e32 v117, 0xbfb8aa3b, v109
	v_exp_f32_e32 v117, v117
	v_lshl_add_u64 v[112:113], v[150:151], 0, v[112:113]
	v_add_f32_e32 v116, 1.0, v116
	v_rcp_f32_e32 v120, v116
	v_add_f32_e32 v117, 1.0, v117
	v_rcp_f32_e32 v121, v117
	v_mul_f32_e32 v116, 0x3fb8aa3b, v108
	v_mul_f32_e32 v117, 0x3fb8aa3b, v109
	v_exp_f32_e32 v116, v116
	v_exp_f32_e32 v117, v117
	v_add_f32_e32 v116, 1.0, v116
	v_add_f32_e32 v117, 1.0, v117
	v_rcp_f32_e32 v116, v116
	v_rcp_f32_e32 v117, v117
	s_waitcnt vmcnt(1)
	v_pk_add_f32 v[130:131], v[96:97], 1.0 op_sel_hi:[1,0] neg_lo:[1,0] neg_hi:[1,0]
	s_waitcnt vmcnt(0)
	v_pk_add_f32 v[118:119], v[100:101], 1.0 op_sel_hi:[1,0] neg_lo:[1,0] neg_hi:[1,0]
	v_pk_add_f32 v[122:123], v[102:103], 1.0 op_sel_hi:[1,0] neg_lo:[1,0] neg_hi:[1,0]
	v_fma_f32 v100, v120, v118, v100
	v_max_f32_e32 v100, 0xda24260, v100
	v_fma_f32 v101, v121, v119, v101
	v_max_f32_e32 v101, 0xda24260, v101
	v_log_f32_e32 v100, v100
	v_mul_f32_e32 v121, 0xbfb8aa3b, v111
	v_exp_f32_e32 v121, v121
	v_pk_add_f32 v[132:133], v[98:99], 1.0 op_sel_hi:[1,0] neg_lo:[1,0] neg_hi:[1,0]
	v_mul_f32_e32 v120, 0x3f317217, v100
	v_fma_f32 v120, v100, s95, -v120
	v_fmac_f32_e32 v120, 0x3377d1cf, v100
	v_fmac_f32_e32 v120, 0x3f317217, v100
	v_cmp_lt_f32_e64 s[46:47], |v100|, s62
	v_add_f32_e32 v121, 1.0, v121
	v_rcp_f32_e32 v125, v121
	v_cndmask_b32_e64 v100, v100, v120, s[46:47]
	v_fmac_f32_e32 v103, v125, v123
	v_log_f32_e32 v101, v101
	v_max_f32_e32 v103, 0xda24260, v103
	v_mul_f32_e32 v125, 0xbfb8aa3b, v107
	v_exp_f32_e32 v125, v125
	v_mul_f32_e32 v120, 0x3f317217, v101
	v_fma_f32 v120, v101, s95, -v120
	v_fmac_f32_e32 v120, 0x3377d1cf, v101
	v_fmac_f32_e32 v120, 0x3f317217, v101
	v_cmp_lt_f32_e64 s[46:47], |v101|, s62
	v_add_f32_e32 v125, 1.0, v125
	v_rcp_f32_e32 v127, v125
	v_cndmask_b32_e64 v101, v101, v120, s[46:47]
	v_mul_f32_e32 v120, 0xbfb8aa3b, v110
	v_exp_f32_e32 v120, v120
	v_mul_f32_e32 v121, 0x3fb8aa3b, v111
	v_mul_f32_e32 v125, 0x3fb8aa3b, v107
	v_exp_f32_e32 v121, v121
	v_add_f32_e32 v120, 1.0, v120
	v_rcp_f32_e32 v124, v120
	v_mul_f32_e32 v120, 0x3fb8aa3b, v110
	v_exp_f32_e32 v120, v120
	v_exp_f32_e32 v125, v125
	v_fma_f32 v102, v124, v122, v102
	v_max_f32_e32 v102, 0xda24260, v102
	v_add_f32_e32 v120, 1.0, v120
	v_add_f32_e32 v121, 1.0, v121
	v_log_f32_e32 v102, v102
	v_add_f32_e32 v125, 1.0, v125
	v_rcp_f32_e32 v120, v120
	v_rcp_f32_e32 v121, v121
	v_mul_f32_e32 v124, 0x3f317217, v102
	v_fma_f32 v124, v102, s95, -v124
	v_fmac_f32_e32 v124, 0x3377d1cf, v102
	v_fmac_f32_e32 v124, 0x3f317217, v102
	v_cmp_lt_f32_e64 s[46:47], |v102|, s62
	v_rcp_f32_e32 v125, v125
	v_pk_mul_f32 v[118:119], v[116:117], v[118:119]
	v_cndmask_b32_e64 v102, v102, v124, s[46:47]
	v_pk_mul_f32 v[116:117], v[120:121], v[122:123]
	v_log_f32_e32 v103, v103
	s_nop 0
	v_mul_f32_e32 v124, 0x3f317217, v103
	v_fma_f32 v124, v103, s95, -v124
	v_fmac_f32_e32 v124, 0x3377d1cf, v103
	v_fmac_f32_e32 v124, 0x3f317217, v103
	v_cmp_lt_f32_e64 s[46:47], |v103|, s62
	s_nop 1
	v_cndmask_b32_e64 v103, v103, v124, s[46:47]
	v_mul_f32_e32 v124, 0xbfb8aa3b, v106
	v_exp_f32_e32 v124, v124
	s_nop 0
	v_add_f32_e32 v124, 1.0, v124
	v_rcp_f32_e32 v126, v124
	v_mul_f32_e32 v124, 0x3fb8aa3b, v106
	v_exp_f32_e32 v124, v124
	v_fma_f32 v96, v126, v130, v96
	v_max_f32_e32 v96, 0xda24260, v96
	v_cmp_gt_f32_e32 vcc, s93, v96
	v_add_f32_e32 v124, 1.0, v124
	v_rcp_f32_e32 v124, v124
	v_cndmask_b32_e64 v126, 0, 32, vcc
	v_ldexp_f32 v96, v96, v126
	v_log_f32_e32 v96, v96
	s_nop 0
	v_mul_f32_e32 v126, 0x3f317217, v96
	v_fma_f32 v126, v96, s95, -v126
	v_fmac_f32_e32 v126, 0x3377d1cf, v96
	v_fmac_f32_e32 v126, 0x3f317217, v96
	v_cmp_lt_f32_e64 s[46:47], |v96|, s62
	s_nop 1
	v_cndmask_b32_e64 v96, v96, v126, s[46:47]
	v_cndmask_b32_e32 v126, 0, v225, vcc
	v_sub_f32_e32 v126, v96, v126
	v_fma_f32 v96, v127, v131, v97
	v_max_f32_e32 v96, 0xda24260, v96
	v_cmp_gt_f32_e32 vcc, s93, v96
	s_nop 1
	v_cndmask_b32_e64 v97, 0, 32, vcc
	v_ldexp_f32 v96, v96, v97
	v_log_f32_e32 v96, v96
	s_nop 0
	v_mul_f32_e32 v97, 0x3f317217, v96
	v_fma_f32 v97, v96, s95, -v97
	v_fmac_f32_e32 v97, 0x3377d1cf, v96
	v_fmac_f32_e32 v97, 0x3f317217, v96
	v_cmp_lt_f32_e64 s[46:47], |v96|, s62
	s_nop 1
	v_cndmask_b32_e64 v96, v96, v97, s[46:47]
	v_cndmask_b32_e32 v97, 0, v225, vcc
	v_sub_f32_e32 v127, v96, v97
	v_mul_f32_e32 v96, 0xbfb8aa3b, v114
	v_exp_f32_e32 v96, v96
	v_mul_f32_e32 v97, 0xbfb8aa3b, v115
	v_exp_f32_e32 v97, v97
	v_add_f32_e32 v96, 1.0, v96
	v_rcp_f32_e32 v128, v96
	v_add_f32_e32 v97, 1.0, v97
	v_rcp_f32_e32 v129, v97
	v_mul_f32_e32 v96, 0x3fb8aa3b, v114
	v_fma_f32 v98, v128, v132, v98
	v_max_f32_e32 v98, 0xda24260, v98
	v_cmp_gt_f32_e32 vcc, s93, v98
	v_fmac_f32_e32 v99, v129, v133
	v_mul_f32_e32 v97, 0x3fb8aa3b, v115
	v_cndmask_b32_e64 v128, 0, 32, vcc
	v_ldexp_f32 v98, v98, v128
	v_log_f32_e32 v98, v98
	v_exp_f32_e32 v96, v96
	v_exp_f32_e32 v97, v97
	v_mul_f32_e32 v128, 0x3f317217, v98
	v_fma_f32 v128, v98, s95, -v128
	v_fmac_f32_e32 v128, 0x3377d1cf, v98
	v_fmac_f32_e32 v128, 0x3f317217, v98
	v_cmp_lt_f32_e64 s[46:47], |v98|, s62
	v_add_f32_e32 v96, 1.0, v96
	v_add_f32_e32 v97, 1.0, v97
	v_cndmask_b32_e64 v98, v98, v128, s[46:47]
	v_cndmask_b32_e32 v128, 0, v225, vcc
	v_sub_f32_e32 v128, v98, v128
	v_max_f32_e32 v98, 0xda24260, v99
	v_cmp_gt_f32_e32 vcc, s93, v98
	v_rcp_f32_e32 v96, v96
	v_rcp_f32_e32 v97, v97
	v_cndmask_b32_e64 v99, 0, 32, vcc
	v_ldexp_f32 v98, v98, v99
	v_log_f32_e32 v98, v98
	v_pk_mul_f32 v[96:97], v[96:97], v[132:133]
	v_mul_f32_e32 v99, 0x3f317217, v98
	v_fma_f32 v99, v98, s95, -v99
	v_fmac_f32_e32 v99, 0x3377d1cf, v98
	v_fmac_f32_e32 v99, 0x3f317217, v98
	v_cmp_lt_f32_e64 s[46:47], |v98|, s62
	s_nop 1
	v_cndmask_b32_e64 v98, v98, v99, s[46:47]
	v_cndmask_b32_e32 v99, 0, v225, vcc
	v_sub_f32_e32 v129, v98, v99
	v_pk_mul_f32 v[98:99], v[124:125], v[130:131]
	global_store_dwordx4 v[112:113], v[100:103], off
	global_store_dwordx4 v[112:113], v[126:129], off offset:16

.LBB0_384:
	s_andn2_b64 vcc, exec, s[36:37]
	s_cbranch_vccnz .LBB0_386
	v_mul_f32_e32 v96, 0xbfb8aa3b, v108
	v_exp_f32_e32 v96, v96
	s_nop 0
	v_add_f32_e32 v96, 1.0, v96
	v_rcp_f32_e32 v118, v96
	v_mul_f32_e32 v96, 0x3fb8aa3b, v108
	v_exp_f32_e32 v96, v96
	s_nop 0
	v_add_f32_e32 v96, 1.0, v96
	v_rcp_f32_e32 v114, v96
	v_mul_f32_e32 v96, 0xbfb8aa3b, v109
	v_exp_f32_e32 v96, v96
	s_nop 0
	v_add_f32_e32 v96, 1.0, v96
	v_rcp_f32_e32 v119, v96
	v_mul_f32_e32 v96, 0x3fb8aa3b, v109
	v_exp_f32_e32 v96, v96
	s_nop 0
	v_add_f32_e32 v96, 1.0, v96
	v_rcp_f32_e32 v115, v96
	global_load_dwordx4 v[96:99], v[148:149], off offset:16
	global_load_dwordx4 v[100:103], v[148:149], off
	s_waitcnt vmcnt(1)
	v_pk_add_f32 v[128:129], v[96:97], 1.0 op_sel_hi:[1,0] neg_lo:[1,0] neg_hi:[1,0]
	s_waitcnt vmcnt(0)
	v_pk_add_f32 v[116:117], v[100:101], 1.0 op_sel_hi:[1,0] neg_lo:[1,0] neg_hi:[1,0]
	v_pk_add_f32 v[120:121], v[102:103], 1.0 op_sel_hi:[1,0] neg_lo:[1,0] neg_hi:[1,0]
	v_fma_f32 v100, v118, v116, v100
	v_max_f32_e32 v100, 0xda24260, v100
	v_fma_f32 v101, v119, v117, v101
	v_max_f32_e32 v101, 0xda24260, v101
	v_log_f32_e32 v100, v100
	v_mul_f32_e32 v119, 0xbfb8aa3b, v111
	v_exp_f32_e32 v119, v119
	v_pk_add_f32 v[130:131], v[98:99], 1.0 op_sel_hi:[1,0] neg_lo:[1,0] neg_hi:[1,0]
	v_mul_f32_e32 v118, 0x3f317217, v100
	v_fma_f32 v118, v100, s95, -v118
	v_fmac_f32_e32 v118, 0x3377d1cf, v100
	v_fmac_f32_e32 v118, 0x3f317217, v100
	v_cmp_lt_f32_e64 s[46:47], |v100|, s62
	v_add_f32_e32 v119, 1.0, v119
	v_rcp_f32_e32 v123, v119
	v_cndmask_b32_e64 v100, v100, v118, s[46:47]
	v_fmac_f32_e32 v103, v123, v121
	v_log_f32_e32 v101, v101
	v_max_f32_e32 v103, 0xda24260, v103
	v_mul_f32_e32 v123, 0xbfb8aa3b, v107
	v_exp_f32_e32 v123, v123
	v_mul_f32_e32 v118, 0x3f317217, v101
	v_fma_f32 v118, v101, s95, -v118
	v_fmac_f32_e32 v118, 0x3377d1cf, v101
	v_fmac_f32_e32 v118, 0x3f317217, v101
	v_cmp_lt_f32_e64 s[46:47], |v101|, s62
	v_add_f32_e32 v123, 1.0, v123
	v_rcp_f32_e32 v125, v123
	v_cndmask_b32_e64 v101, v101, v118, s[46:47]
	v_mul_f32_e32 v118, 0xbfb8aa3b, v110
	v_exp_f32_e32 v118, v118
	v_mul_f32_e32 v119, 0x3fb8aa3b, v111
	v_mul_f32_e32 v123, 0x3fb8aa3b, v107
	v_exp_f32_e32 v119, v119
	v_add_f32_e32 v118, 1.0, v118
	v_rcp_f32_e32 v122, v118
	v_mul_f32_e32 v118, 0x3fb8aa3b, v110
	v_exp_f32_e32 v118, v118
	v_exp_f32_e32 v123, v123
	v_fma_f32 v102, v122, v120, v102
	v_max_f32_e32 v102, 0xda24260, v102
	v_add_f32_e32 v118, 1.0, v118
	v_add_f32_e32 v119, 1.0, v119
	v_log_f32_e32 v102, v102
	v_add_f32_e32 v123, 1.0, v123
	v_rcp_f32_e32 v118, v118
	v_rcp_f32_e32 v119, v119
	v_mul_f32_e32 v122, 0x3f317217, v102
	v_fma_f32 v122, v102, s95, -v122
	v_fmac_f32_e32 v122, 0x3377d1cf, v102
	v_fmac_f32_e32 v122, 0x3f317217, v102
	v_cmp_lt_f32_e64 s[46:47], |v102|, s62
	v_rcp_f32_e32 v123, v123
	v_pk_mul_f32 v[116:117], v[114:115], v[116:117]
	v_cndmask_b32_e64 v102, v102, v122, s[46:47]
	v_pk_mul_f32 v[114:115], v[118:119], v[120:121]
	v_log_f32_e32 v103, v103
	v_lshl_add_u64 v[118:119], v[146:147], 0, v[104:105]
	v_mul_f32_e32 v122, 0x3f317217, v103
	v_fma_f32 v122, v103, s95, -v122
	v_fmac_f32_e32 v122, 0x3377d1cf, v103
	v_fmac_f32_e32 v122, 0x3f317217, v103
	v_cmp_lt_f32_e64 s[46:47], |v103|, s62
	s_nop 1
	v_cndmask_b32_e64 v103, v103, v122, s[46:47]
	v_mul_f32_e32 v122, 0xbfb8aa3b, v106
	v_exp_f32_e32 v122, v122
	s_nop 0
	v_add_f32_e32 v122, 1.0, v122
	v_rcp_f32_e32 v124, v122
	v_mul_f32_e32 v122, 0x3fb8aa3b, v106
	v_exp_f32_e32 v122, v122
	v_fma_f32 v96, v124, v128, v96
	v_max_f32_e32 v96, 0xda24260, v96
	v_cmp_gt_f32_e32 vcc, s93, v96
	v_add_f32_e32 v122, 1.0, v122
	v_rcp_f32_e32 v122, v122
	v_cndmask_b32_e64 v124, 0, 32, vcc
	v_ldexp_f32 v96, v96, v124
	v_log_f32_e32 v96, v96
	s_nop 0
	v_mul_f32_e32 v124, 0x3f317217, v96
	v_fma_f32 v124, v96, s95, -v124
	v_fmac_f32_e32 v124, 0x3377d1cf, v96
	v_fmac_f32_e32 v124, 0x3f317217, v96
	v_cmp_lt_f32_e64 s[46:47], |v96|, s62
	s_nop 1
	v_cndmask_b32_e64 v96, v96, v124, s[46:47]
	v_cndmask_b32_e32 v124, 0, v225, vcc
	v_sub_f32_e32 v124, v96, v124
	v_fma_f32 v96, v125, v129, v97
	v_max_f32_e32 v96, 0xda24260, v96
	v_cmp_gt_f32_e32 vcc, s93, v96
	s_nop 1
	v_cndmask_b32_e64 v97, 0, 32, vcc
	v_ldexp_f32 v96, v96, v97
	v_log_f32_e32 v96, v96
	s_nop 0
	v_mul_f32_e32 v97, 0x3f317217, v96
	v_fma_f32 v97, v96, s95, -v97
	v_fmac_f32_e32 v97, 0x3377d1cf, v96
	v_fmac_f32_e32 v97, 0x3f317217, v96
	v_cmp_lt_f32_e64 s[46:47], |v96|, s62
	s_nop 1
	v_cndmask_b32_e64 v96, v96, v97, s[46:47]
	v_cndmask_b32_e32 v97, 0, v225, vcc
	v_sub_f32_e32 v125, v96, v97
	v_mul_f32_e32 v96, 0xbfb8aa3b, v112
	v_exp_f32_e32 v96, v96
	v_mul_f32_e32 v97, 0xbfb8aa3b, v113
	v_exp_f32_e32 v97, v97
	v_add_f32_e32 v96, 1.0, v96
	v_rcp_f32_e32 v126, v96
	v_add_f32_e32 v97, 1.0, v97
	v_rcp_f32_e32 v127, v97
	v_mul_f32_e32 v96, 0x3fb8aa3b, v112
	v_fma_f32 v98, v126, v130, v98
	v_max_f32_e32 v98, 0xda24260, v98
	v_cmp_gt_f32_e32 vcc, s93, v98
	v_fmac_f32_e32 v99, v127, v131
	v_mul_f32_e32 v97, 0x3fb8aa3b, v113
	v_cndmask_b32_e64 v126, 0, 32, vcc
	v_ldexp_f32 v98, v98, v126
	v_log_f32_e32 v98, v98
	v_exp_f32_e32 v96, v96
	v_exp_f32_e32 v97, v97
	v_mul_f32_e32 v126, 0x3f317217, v98
	v_fma_f32 v126, v98, s95, -v126
	v_fmac_f32_e32 v126, 0x3377d1cf, v98
	v_fmac_f32_e32 v126, 0x3f317217, v98
	v_cmp_lt_f32_e64 s[46:47], |v98|, s62
	v_add_f32_e32 v96, 1.0, v96
	v_add_f32_e32 v97, 1.0, v97
	v_cndmask_b32_e64 v98, v98, v126, s[46:47]
	v_cndmask_b32_e32 v126, 0, v225, vcc
	v_sub_f32_e32 v126, v98, v126
	v_max_f32_e32 v98, 0xda24260, v99
	v_cmp_gt_f32_e32 vcc, s93, v98
	v_rcp_f32_e32 v96, v96
	v_rcp_f32_e32 v97, v97
	v_cndmask_b32_e64 v99, 0, 32, vcc
	v_ldexp_f32 v98, v98, v99
	v_log_f32_e32 v98, v98
	v_pk_mul_f32 v[96:97], v[96:97], v[130:131]
	v_mul_f32_e32 v99, 0x3f317217, v98
	v_fma_f32 v99, v98, s95, -v99
	v_fmac_f32_e32 v99, 0x3377d1cf, v98
	v_fmac_f32_e32 v99, 0x3f317217, v98
	v_cmp_lt_f32_e64 s[46:47], |v98|, s62
	s_nop 1
	v_cndmask_b32_e64 v98, v98, v99, s[46:47]
	v_cndmask_b32_e32 v99, 0, v225, vcc
	v_sub_f32_e32 v127, v98, v99
	v_pk_mul_f32 v[98:99], v[122:123], v[128:129]
	global_store_dwordx4 v[118:119], v[100:103], off
	global_store_dwordx4 v[118:119], v[124:127], off offset:16

.LBB0_396:
	s_andn2_b64 vcc, exec, s[36:37]
	s_cbranch_vccnz .LBB0_398
	global_load_dwordx4 v[88:91], v[148:149], off offset:528
	global_load_dwordx4 v[92:95], v[148:149], off offset:512
	v_mul_f32_e32 v108, 0xbfb8aa3b, v100
	v_exp_f32_e32 v108, v108
	v_mul_f32_e32 v109, 0xbfb8aa3b, v101
	v_exp_f32_e32 v109, v109
	v_lshl_add_u64 v[104:105], v[150:151], 0, v[104:105]
	v_add_f32_e32 v108, 1.0, v108
	v_rcp_f32_e32 v112, v108
	v_add_f32_e32 v109, 1.0, v109
	v_rcp_f32_e32 v113, v109
	v_mul_f32_e32 v108, 0x3fb8aa3b, v100
	v_mul_f32_e32 v109, 0x3fb8aa3b, v101
	v_exp_f32_e32 v108, v108
	v_exp_f32_e32 v109, v109
	v_add_f32_e32 v108, 1.0, v108
	v_add_f32_e32 v109, 1.0, v109
	v_rcp_f32_e32 v108, v108
	v_rcp_f32_e32 v109, v109
	s_waitcnt vmcnt(1)
	v_pk_add_f32 v[122:123], v[88:89], 1.0 op_sel_hi:[1,0] neg_lo:[1,0] neg_hi:[1,0]
	s_waitcnt vmcnt(0)
	v_pk_add_f32 v[110:111], v[92:93], 1.0 op_sel_hi:[1,0] neg_lo:[1,0] neg_hi:[1,0]
	v_pk_add_f32 v[114:115], v[94:95], 1.0 op_sel_hi:[1,0] neg_lo:[1,0] neg_hi:[1,0]
	v_fma_f32 v92, v112, v110, v92
	v_max_f32_e32 v92, 0xda24260, v92
	v_fma_f32 v93, v113, v111, v93
	v_max_f32_e32 v93, 0xda24260, v93
	v_log_f32_e32 v92, v92
	v_mul_f32_e32 v113, 0xbfb8aa3b, v103
	v_exp_f32_e32 v113, v113
	v_pk_add_f32 v[124:125], v[90:91], 1.0 op_sel_hi:[1,0] neg_lo:[1,0] neg_hi:[1,0]
	v_mul_f32_e32 v112, 0x3f317217, v92
	v_fma_f32 v112, v92, s95, -v112
	v_fmac_f32_e32 v112, 0x3377d1cf, v92
	v_fmac_f32_e32 v112, 0x3f317217, v92
	v_cmp_lt_f32_e64 s[46:47], |v92|, s62
	v_add_f32_e32 v113, 1.0, v113
	v_rcp_f32_e32 v117, v113
	v_cndmask_b32_e64 v92, v92, v112, s[46:47]
	v_fmac_f32_e32 v95, v117, v115
	v_log_f32_e32 v93, v93
	v_max_f32_e32 v95, 0xda24260, v95
	v_mul_f32_e32 v117, 0xbfb8aa3b, v99
	v_exp_f32_e32 v117, v117
	v_mul_f32_e32 v112, 0x3f317217, v93
	v_fma_f32 v112, v93, s95, -v112
	v_fmac_f32_e32 v112, 0x3377d1cf, v93
	v_fmac_f32_e32 v112, 0x3f317217, v93
	v_cmp_lt_f32_e64 s[46:47], |v93|, s62
	v_add_f32_e32 v117, 1.0, v117
	v_rcp_f32_e32 v119, v117
	v_cndmask_b32_e64 v93, v93, v112, s[46:47]
	v_mul_f32_e32 v112, 0xbfb8aa3b, v102
	v_exp_f32_e32 v112, v112
	v_mul_f32_e32 v113, 0x3fb8aa3b, v103
	v_mul_f32_e32 v117, 0x3fb8aa3b, v99
	v_exp_f32_e32 v113, v113
	v_add_f32_e32 v112, 1.0, v112
	v_rcp_f32_e32 v116, v112
	v_mul_f32_e32 v112, 0x3fb8aa3b, v102
	v_exp_f32_e32 v112, v112
	v_exp_f32_e32 v117, v117
	v_fma_f32 v94, v116, v114, v94
	v_max_f32_e32 v94, 0xda24260, v94
	v_add_f32_e32 v112, 1.0, v112
	v_add_f32_e32 v113, 1.0, v113
	v_log_f32_e32 v94, v94
	v_add_f32_e32 v117, 1.0, v117
	v_rcp_f32_e32 v112, v112
	v_rcp_f32_e32 v113, v113
	v_mul_f32_e32 v116, 0x3f317217, v94
	v_fma_f32 v116, v94, s95, -v116
	v_fmac_f32_e32 v116, 0x3377d1cf, v94
	v_fmac_f32_e32 v116, 0x3f317217, v94
	v_cmp_lt_f32_e64 s[46:47], |v94|, s62
	v_rcp_f32_e32 v117, v117
	v_pk_mul_f32 v[110:111], v[108:109], v[110:111]
	v_cndmask_b32_e64 v94, v94, v116, s[46:47]
	v_pk_mul_f32 v[108:109], v[112:113], v[114:115]
	v_log_f32_e32 v95, v95
	s_nop 0
	v_mul_f32_e32 v116, 0x3f317217, v95
	v_fma_f32 v116, v95, s95, -v116
	v_fmac_f32_e32 v116, 0x3377d1cf, v95
	v_fmac_f32_e32 v116, 0x3f317217, v95
	v_cmp_lt_f32_e64 s[46:47], |v95|, s62
	s_nop 1
	v_cndmask_b32_e64 v95, v95, v116, s[46:47]
	v_mul_f32_e32 v116, 0xbfb8aa3b, v98
	v_exp_f32_e32 v116, v116
	s_nop 0
	v_add_f32_e32 v116, 1.0, v116
	v_rcp_f32_e32 v118, v116
	v_mul_f32_e32 v116, 0x3fb8aa3b, v98
	v_exp_f32_e32 v116, v116
	v_fma_f32 v88, v118, v122, v88
	v_max_f32_e32 v88, 0xda24260, v88
	v_cmp_gt_f32_e32 vcc, s93, v88
	v_add_f32_e32 v116, 1.0, v116
	v_rcp_f32_e32 v116, v116
	v_cndmask_b32_e64 v118, 0, 32, vcc
	v_ldexp_f32 v88, v88, v118
	v_log_f32_e32 v88, v88
	s_nop 0
	v_mul_f32_e32 v118, 0x3f317217, v88
	v_fma_f32 v118, v88, s95, -v118
	v_fmac_f32_e32 v118, 0x3377d1cf, v88
	v_fmac_f32_e32 v118, 0x3f317217, v88
	v_cmp_lt_f32_e64 s[46:47], |v88|, s62
	s_nop 1
	v_cndmask_b32_e64 v88, v88, v118, s[46:47]
	v_cndmask_b32_e32 v118, 0, v225, vcc
	v_sub_f32_e32 v118, v88, v118
	v_fma_f32 v88, v119, v123, v89
	v_max_f32_e32 v88, 0xda24260, v88
	v_cmp_gt_f32_e32 vcc, s93, v88
	s_nop 1
	v_cndmask_b32_e64 v89, 0, 32, vcc
	v_ldexp_f32 v88, v88, v89
	v_log_f32_e32 v88, v88
	s_nop 0
	v_mul_f32_e32 v89, 0x3f317217, v88
	v_fma_f32 v89, v88, s95, -v89
	v_fmac_f32_e32 v89, 0x3377d1cf, v88
	v_fmac_f32_e32 v89, 0x3f317217, v88
	v_cmp_lt_f32_e64 s[46:47], |v88|, s62
	s_nop 1
	v_cndmask_b32_e64 v88, v88, v89, s[46:47]
	v_cndmask_b32_e32 v89, 0, v225, vcc
	v_sub_f32_e32 v119, v88, v89
	v_mul_f32_e32 v88, 0xbfb8aa3b, v106
	v_exp_f32_e32 v88, v88
	v_mul_f32_e32 v89, 0xbfb8aa3b, v107
	v_exp_f32_e32 v89, v89
	v_add_f32_e32 v88, 1.0, v88
	v_rcp_f32_e32 v120, v88
	v_add_f32_e32 v89, 1.0, v89
	v_rcp_f32_e32 v121, v89
	v_mul_f32_e32 v88, 0x3fb8aa3b, v106
	v_fma_f32 v90, v120, v124, v90
	v_max_f32_e32 v90, 0xda24260, v90
	v_cmp_gt_f32_e32 vcc, s93, v90
	v_fmac_f32_e32 v91, v121, v125
	v_mul_f32_e32 v89, 0x3fb8aa3b, v107
	v_cndmask_b32_e64 v120, 0, 32, vcc
	v_ldexp_f32 v90, v90, v120
	v_log_f32_e32 v90, v90
	v_exp_f32_e32 v88, v88
	v_exp_f32_e32 v89, v89
	v_mul_f32_e32 v120, 0x3f317217, v90
	v_fma_f32 v120, v90, s95, -v120
	v_fmac_f32_e32 v120, 0x3377d1cf, v90
	v_fmac_f32_e32 v120, 0x3f317217, v90
	v_cmp_lt_f32_e64 s[46:47], |v90|, s62
	v_add_f32_e32 v88, 1.0, v88
	v_add_f32_e32 v89, 1.0, v89
	v_cndmask_b32_e64 v90, v90, v120, s[46:47]
	v_cndmask_b32_e32 v120, 0, v225, vcc
	v_sub_f32_e32 v120, v90, v120
	v_max_f32_e32 v90, 0xda24260, v91
	v_cmp_gt_f32_e32 vcc, s93, v90
	v_rcp_f32_e32 v88, v88
	v_rcp_f32_e32 v89, v89
	v_cndmask_b32_e64 v91, 0, 32, vcc
	v_ldexp_f32 v90, v90, v91
	v_log_f32_e32 v90, v90
	v_pk_mul_f32 v[88:89], v[88:89], v[124:125]
	v_mul_f32_e32 v91, 0x3f317217, v90
	v_fma_f32 v91, v90, s95, -v91
	v_fmac_f32_e32 v91, 0x3377d1cf, v90
	v_fmac_f32_e32 v91, 0x3f317217, v90
	v_cmp_lt_f32_e64 s[46:47], |v90|, s62
	s_nop 1
	v_cndmask_b32_e64 v90, v90, v91, s[46:47]
	v_cndmask_b32_e32 v91, 0, v225, vcc
	v_sub_f32_e32 v121, v90, v91
	v_pk_mul_f32 v[90:91], v[116:117], v[122:123]
	global_store_dwordx4 v[104:105], v[92:95], off
	global_store_dwordx4 v[104:105], v[118:121], off offset:16

.LBB0_408:
	s_andn2_b64 vcc, exec, s[36:37]
	s_cbranch_vccnz .LBB0_410
	v_mul_f32_e32 v88, 0xbfb8aa3b, v102
	v_exp_f32_e32 v88, v88
	v_mul_f32_e32 v113, 0xbfb8aa3b, v105
	v_exp_f32_e32 v113, v113
	v_mul_f32_e32 v117, 0xbfb8aa3b, v101
	v_add_f32_e32 v88, 1.0, v88
	v_rcp_f32_e32 v99, v88
	v_mul_f32_e32 v88, 0x3fb8aa3b, v102
	v_exp_f32_e32 v88, v88
	v_add_f32_e32 v113, 1.0, v113
	v_rcp_f32_e32 v116, v113
	v_exp_f32_e32 v117, v117
	v_add_f32_e32 v88, 1.0, v88
	v_rcp_f32_e32 v108, v88
	v_mul_f32_e32 v88, 0xbfb8aa3b, v103
	v_exp_f32_e32 v88, v88
	v_add_f32_e32 v117, 1.0, v117
	v_rcp_f32_e32 v119, v117
	v_mul_f32_e32 v113, 0x3fb8aa3b, v105
	v_add_f32_e32 v88, 1.0, v88
	v_rcp_f32_e32 v112, v88
	v_mul_f32_e32 v88, 0x3fb8aa3b, v103
	v_exp_f32_e32 v88, v88
	v_mul_f32_e32 v117, 0x3fb8aa3b, v101
	v_exp_f32_e32 v113, v113
	v_exp_f32_e32 v117, v117
	v_add_f32_e32 v88, 1.0, v88
	v_rcp_f32_e32 v109, v88
	global_load_dwordx4 v[88:91], v[148:149], off offset:16
	global_load_dwordx4 v[92:95], v[148:149], off
	v_add_f32_e32 v113, 1.0, v113
	v_add_f32_e32 v117, 1.0, v117
	v_rcp_f32_e32 v113, v113
	v_rcp_f32_e32 v117, v117
	s_waitcnt vmcnt(1)
	v_pk_add_f32 v[122:123], v[88:89], 1.0 op_sel_hi:[1,0] neg_lo:[1,0] neg_hi:[1,0]
	s_waitcnt vmcnt(0)
	v_pk_add_f32 v[110:111], v[92:93], 1.0 op_sel_hi:[1,0] neg_lo:[1,0] neg_hi:[1,0]
	v_pk_add_f32 v[114:115], v[94:95], 1.0 op_sel_hi:[1,0] neg_lo:[1,0] neg_hi:[1,0]
	v_fma_f32 v92, v99, v110, v92
	v_max_f32_e32 v92, 0xda24260, v92
	v_fma_f32 v93, v112, v111, v93
	v_max_f32_e32 v93, 0xda24260, v93
	v_log_f32_e32 v92, v92
	v_fmac_f32_e32 v95, v116, v115
	v_max_f32_e32 v95, 0xda24260, v95
	v_pk_add_f32 v[124:125], v[90:91], 1.0 op_sel_hi:[1,0] neg_lo:[1,0] neg_hi:[1,0]
	v_mul_f32_e32 v99, 0x3f317217, v92
	v_fma_f32 v99, v92, s95, -v99
	v_fmac_f32_e32 v99, 0x3377d1cf, v92
	v_fmac_f32_e32 v99, 0x3f317217, v92
	v_cmp_lt_f32_e64 s[46:47], |v92|, s62
	v_mul_f32_e32 v112, 0x3fb8aa3b, v104
	v_mul_f32_e32 v116, 0x3fb8aa3b, v100
	v_cndmask_b32_e64 v92, v92, v99, s[46:47]
	v_exp_f32_e32 v112, v112
	v_log_f32_e32 v93, v93
	v_exp_f32_e32 v116, v116
	v_add_f32_e32 v112, 1.0, v112
	v_rcp_f32_e32 v112, v112
	v_mul_f32_e32 v99, 0x3f317217, v93
	v_fma_f32 v99, v93, s95, -v99
	v_fmac_f32_e32 v99, 0x3377d1cf, v93
	v_fmac_f32_e32 v99, 0x3f317217, v93
	v_cmp_lt_f32_e64 s[46:47], |v93|, s62
	v_add_f32_e32 v116, 1.0, v116
	v_rcp_f32_e32 v116, v116
	v_cndmask_b32_e64 v93, v93, v99, s[46:47]
	v_mul_f32_e32 v99, 0xbfb8aa3b, v104
	v_exp_f32_e32 v99, v99
	v_pk_mul_f32 v[110:111], v[108:109], v[110:111]
	v_pk_mul_f32 v[108:109], v[112:113], v[114:115]
	v_lshl_add_u64 v[112:113], v[146:147], 0, v[96:97]
	v_add_f32_e32 v99, 1.0, v99
	v_rcp_f32_e32 v99, v99
	s_nop 0
	v_fma_f32 v94, v99, v114, v94
	v_max_f32_e32 v94, 0xda24260, v94
	s_nop 1
	v_log_f32_e32 v94, v94
	s_nop 0
	v_mul_f32_e32 v99, 0x3f317217, v94
	v_fma_f32 v99, v94, s95, -v99
	v_fmac_f32_e32 v99, 0x3377d1cf, v94
	v_fmac_f32_e32 v99, 0x3f317217, v94
	v_cmp_lt_f32_e64 s[46:47], |v94|, s62
	s_nop 1
	v_cndmask_b32_e64 v94, v94, v99, s[46:47]
	s_nop 0
	v_log_f32_e32 v95, v95
	s_nop 0
	v_mul_f32_e32 v99, 0x3f317217, v95
	v_fma_f32 v99, v95, s95, -v99
	v_fmac_f32_e32 v99, 0x3377d1cf, v95
	v_fmac_f32_e32 v99, 0x3f317217, v95
	v_cmp_lt_f32_e64 s[46:47], |v95|, s62
	s_nop 1
	v_cndmask_b32_e64 v95, v95, v99, s[46:47]
	v_mul_f32_e32 v99, 0xbfb8aa3b, v100
	v_exp_f32_e32 v99, v99
	s_nop 0
	v_add_f32_e32 v99, 1.0, v99
	v_rcp_f32_e32 v99, v99
	s_nop 0
	v_fma_f32 v88, v99, v122, v88
	v_max_f32_e32 v88, 0xda24260, v88
	v_cmp_gt_f32_e32 vcc, s93, v88
	s_nop 1
	v_cndmask_b32_e64 v99, 0, 32, vcc
	v_ldexp_f32 v88, v88, v99
	v_log_f32_e32 v88, v88
	s_nop 0
	v_mul_f32_e32 v99, 0x3f317217, v88
	v_fma_f32 v99, v88, s95, -v99
	v_fmac_f32_e32 v99, 0x3377d1cf, v88
	v_fmac_f32_e32 v99, 0x3f317217, v88
	v_cmp_lt_f32_e64 s[46:47], |v88|, s62
	s_nop 1
	v_cndmask_b32_e64 v88, v88, v99, s[46:47]
	v_cndmask_b32_e32 v99, 0, v225, vcc
	v_sub_f32_e32 v118, v88, v99
	v_fma_f32 v88, v119, v123, v89
	v_max_f32_e32 v88, 0xda24260, v88
	v_cmp_gt_f32_e32 vcc, s93, v88
	s_nop 1
	v_cndmask_b32_e64 v89, 0, 32, vcc
	v_ldexp_f32 v88, v88, v89
	v_log_f32_e32 v88, v88
	s_nop 0
	v_mul_f32_e32 v89, 0x3f317217, v88
	v_fma_f32 v89, v88, s95, -v89
	v_fmac_f32_e32 v89, 0x3377d1cf, v88
	v_fmac_f32_e32 v89, 0x3f317217, v88
	v_cmp_lt_f32_e64 s[46:47], |v88|, s62
	s_nop 1
	v_cndmask_b32_e64 v88, v88, v89, s[46:47]
	v_cndmask_b32_e32 v89, 0, v225, vcc
	v_sub_f32_e32 v119, v88, v89
	v_mul_f32_e32 v88, 0xbfb8aa3b, v106
	v_exp_f32_e32 v88, v88
	v_mul_f32_e32 v89, 0xbfb8aa3b, v107
	v_exp_f32_e32 v89, v89
	v_add_f32_e32 v88, 1.0, v88
	v_rcp_f32_e32 v99, v88
	v_add_f32_e32 v89, 1.0, v89
	v_rcp_f32_e32 v121, v89
	v_mul_f32_e32 v88, 0x3fb8aa3b, v106
	v_fma_f32 v90, v99, v124, v90
	v_max_f32_e32 v90, 0xda24260, v90
	v_cmp_gt_f32_e32 vcc, s93, v90
	v_fmac_f32_e32 v91, v121, v125
	v_mul_f32_e32 v89, 0x3fb8aa3b, v107
	v_cndmask_b32_e64 v99, 0, 32, vcc
	v_ldexp_f32 v90, v90, v99
	v_log_f32_e32 v90, v90
	v_exp_f32_e32 v88, v88
	v_exp_f32_e32 v89, v89
	v_mul_f32_e32 v99, 0x3f317217, v90
	v_fma_f32 v99, v90, s95, -v99
	v_fmac_f32_e32 v99, 0x3377d1cf, v90
	v_fmac_f32_e32 v99, 0x3f317217, v90
	v_cmp_lt_f32_e64 s[46:47], |v90|, s62
	v_add_f32_e32 v88, 1.0, v88
	v_add_f32_e32 v89, 1.0, v89
	v_cndmask_b32_e64 v90, v90, v99, s[46:47]
	v_cndmask_b32_e32 v99, 0, v225, vcc
	v_sub_f32_e32 v120, v90, v99
	v_max_f32_e32 v90, 0xda24260, v91
	v_cmp_gt_f32_e32 vcc, s93, v90
	v_rcp_f32_e32 v88, v88
	v_rcp_f32_e32 v89, v89
	v_cndmask_b32_e64 v91, 0, 32, vcc
	v_ldexp_f32 v90, v90, v91
	v_log_f32_e32 v90, v90
	v_pk_mul_f32 v[88:89], v[88:89], v[124:125]
	v_mul_f32_e32 v91, 0x3f317217, v90
	v_fma_f32 v91, v90, s95, -v91
	v_fmac_f32_e32 v91, 0x3377d1cf, v90
	v_fmac_f32_e32 v91, 0x3f317217, v90
	v_cmp_lt_f32_e64 s[46:47], |v90|, s62
	s_nop 1
	v_cndmask_b32_e64 v90, v90, v91, s[46:47]
	v_cndmask_b32_e32 v91, 0, v225, vcc
	v_sub_f32_e32 v121, v90, v91
	v_pk_mul_f32 v[90:91], v[116:117], v[122:123]
	global_store_dwordx4 v[112:113], v[92:95], off
	global_store_dwordx4 v[112:113], v[118:121], off offset:16

.LBB0_420:
	s_andn2_b64 vcc, exec, s[36:37]
	s_cbranch_vccnz .LBB0_422
	global_load_dwordx4 v[80:83], v[148:149], off offset:528
	global_load_dwordx4 v[84:87], v[148:149], off offset:512
	v_mul_f32_e32 v100, 0xbfb8aa3b, v92
	v_exp_f32_e32 v100, v100
	v_mul_f32_e32 v101, 0xbfb8aa3b, v93
	v_exp_f32_e32 v101, v101
	v_lshl_add_u64 v[96:97], v[150:151], 0, v[96:97]
	v_add_f32_e32 v100, 1.0, v100
	v_rcp_f32_e32 v104, v100
	v_add_f32_e32 v101, 1.0, v101
	v_rcp_f32_e32 v105, v101
	v_mul_f32_e32 v100, 0x3fb8aa3b, v92
	v_mul_f32_e32 v101, 0x3fb8aa3b, v93
	v_exp_f32_e32 v100, v100
	v_exp_f32_e32 v101, v101
	v_add_f32_e32 v100, 1.0, v100
	v_add_f32_e32 v101, 1.0, v101
	v_rcp_f32_e32 v100, v100
	v_rcp_f32_e32 v101, v101
	s_waitcnt vmcnt(1)
	v_pk_add_f32 v[114:115], v[80:81], 1.0 op_sel_hi:[1,0] neg_lo:[1,0] neg_hi:[1,0]
	s_waitcnt vmcnt(0)
	v_pk_add_f32 v[102:103], v[84:85], 1.0 op_sel_hi:[1,0] neg_lo:[1,0] neg_hi:[1,0]
	v_pk_add_f32 v[106:107], v[86:87], 1.0 op_sel_hi:[1,0] neg_lo:[1,0] neg_hi:[1,0]
	v_fma_f32 v84, v104, v102, v84
	v_max_f32_e32 v84, 0xda24260, v84
	v_fma_f32 v85, v105, v103, v85
	v_max_f32_e32 v85, 0xda24260, v85
	v_log_f32_e32 v84, v84
	v_mul_f32_e32 v105, 0xbfb8aa3b, v95
	v_exp_f32_e32 v105, v105
	v_pk_add_f32 v[116:117], v[82:83], 1.0 op_sel_hi:[1,0] neg_lo:[1,0] neg_hi:[1,0]
	v_mul_f32_e32 v104, 0x3f317217, v84
	v_fma_f32 v104, v84, s95, -v104
	v_fmac_f32_e32 v104, 0x3377d1cf, v84
	v_fmac_f32_e32 v104, 0x3f317217, v84
	v_cmp_lt_f32_e64 s[46:47], |v84|, s62
	v_add_f32_e32 v105, 1.0, v105
	v_rcp_f32_e32 v109, v105
	v_cndmask_b32_e64 v84, v84, v104, s[46:47]
	v_fmac_f32_e32 v87, v109, v107
	v_log_f32_e32 v85, v85
	v_max_f32_e32 v87, 0xda24260, v87
	v_mul_f32_e32 v109, 0xbfb8aa3b, v91
	v_exp_f32_e32 v109, v109
	v_mul_f32_e32 v104, 0x3f317217, v85
	v_fma_f32 v104, v85, s95, -v104
	v_fmac_f32_e32 v104, 0x3377d1cf, v85
	v_fmac_f32_e32 v104, 0x3f317217, v85
	v_cmp_lt_f32_e64 s[46:47], |v85|, s62
	v_add_f32_e32 v109, 1.0, v109
	v_rcp_f32_e32 v111, v109
	v_cndmask_b32_e64 v85, v85, v104, s[46:47]
	v_mul_f32_e32 v104, 0xbfb8aa3b, v94
	v_exp_f32_e32 v104, v104
	v_mul_f32_e32 v105, 0x3fb8aa3b, v95
	v_mul_f32_e32 v109, 0x3fb8aa3b, v91
	v_exp_f32_e32 v105, v105
	v_add_f32_e32 v104, 1.0, v104
	v_rcp_f32_e32 v108, v104
	v_mul_f32_e32 v104, 0x3fb8aa3b, v94
	v_exp_f32_e32 v104, v104
	v_exp_f32_e32 v109, v109
	v_fma_f32 v86, v108, v106, v86
	v_max_f32_e32 v86, 0xda24260, v86
	v_add_f32_e32 v104, 1.0, v104
	v_add_f32_e32 v105, 1.0, v105
	v_log_f32_e32 v86, v86
	v_add_f32_e32 v109, 1.0, v109
	v_rcp_f32_e32 v104, v104
	v_rcp_f32_e32 v105, v105
	v_mul_f32_e32 v108, 0x3f317217, v86
	v_fma_f32 v108, v86, s95, -v108
	v_fmac_f32_e32 v108, 0x3377d1cf, v86
	v_fmac_f32_e32 v108, 0x3f317217, v86
	v_cmp_lt_f32_e64 s[46:47], |v86|, s62
	v_rcp_f32_e32 v109, v109
	v_pk_mul_f32 v[102:103], v[100:101], v[102:103]
	v_cndmask_b32_e64 v86, v86, v108, s[46:47]
	v_pk_mul_f32 v[100:101], v[104:105], v[106:107]
	v_log_f32_e32 v87, v87
	s_nop 0
	v_mul_f32_e32 v108, 0x3f317217, v87
	v_fma_f32 v108, v87, s95, -v108
	v_fmac_f32_e32 v108, 0x3377d1cf, v87
	v_fmac_f32_e32 v108, 0x3f317217, v87
	v_cmp_lt_f32_e64 s[46:47], |v87|, s62
	s_nop 1
	v_cndmask_b32_e64 v87, v87, v108, s[46:47]
	v_mul_f32_e32 v108, 0xbfb8aa3b, v90
	v_exp_f32_e32 v108, v108
	s_nop 0
	v_add_f32_e32 v108, 1.0, v108
	v_rcp_f32_e32 v110, v108
	v_mul_f32_e32 v108, 0x3fb8aa3b, v90
	v_exp_f32_e32 v108, v108
	v_fma_f32 v80, v110, v114, v80
	v_max_f32_e32 v80, 0xda24260, v80
	v_cmp_gt_f32_e32 vcc, s93, v80
	v_add_f32_e32 v108, 1.0, v108
	v_rcp_f32_e32 v108, v108
	v_cndmask_b32_e64 v110, 0, 32, vcc
	v_ldexp_f32 v80, v80, v110
	v_log_f32_e32 v80, v80
	s_nop 0
	v_mul_f32_e32 v110, 0x3f317217, v80
	v_fma_f32 v110, v80, s95, -v110
	v_fmac_f32_e32 v110, 0x3377d1cf, v80
	v_fmac_f32_e32 v110, 0x3f317217, v80
	v_cmp_lt_f32_e64 s[46:47], |v80|, s62
	s_nop 1
	v_cndmask_b32_e64 v80, v80, v110, s[46:47]
	v_cndmask_b32_e32 v110, 0, v225, vcc
	v_sub_f32_e32 v110, v80, v110
	v_fma_f32 v80, v111, v115, v81
	v_max_f32_e32 v80, 0xda24260, v80
	v_cmp_gt_f32_e32 vcc, s93, v80
	s_nop 1
	v_cndmask_b32_e64 v81, 0, 32, vcc
	v_ldexp_f32 v80, v80, v81
	v_log_f32_e32 v80, v80
	s_nop 0
	v_mul_f32_e32 v81, 0x3f317217, v80
	v_fma_f32 v81, v80, s95, -v81
	v_fmac_f32_e32 v81, 0x3377d1cf, v80
	v_fmac_f32_e32 v81, 0x3f317217, v80
	v_cmp_lt_f32_e64 s[46:47], |v80|, s62
	s_nop 1
	v_cndmask_b32_e64 v80, v80, v81, s[46:47]
	v_cndmask_b32_e32 v81, 0, v225, vcc
	v_sub_f32_e32 v111, v80, v81
	v_mul_f32_e32 v80, 0xbfb8aa3b, v98
	v_exp_f32_e32 v80, v80
	v_mul_f32_e32 v81, 0xbfb8aa3b, v99
	v_exp_f32_e32 v81, v81
	v_add_f32_e32 v80, 1.0, v80
	v_rcp_f32_e32 v112, v80
	v_add_f32_e32 v81, 1.0, v81
	v_rcp_f32_e32 v113, v81
	v_mul_f32_e32 v80, 0x3fb8aa3b, v98
	v_fma_f32 v82, v112, v116, v82
	v_max_f32_e32 v82, 0xda24260, v82
	v_cmp_gt_f32_e32 vcc, s93, v82
	v_fmac_f32_e32 v83, v113, v117
	v_mul_f32_e32 v81, 0x3fb8aa3b, v99
	v_cndmask_b32_e64 v112, 0, 32, vcc
	v_ldexp_f32 v82, v82, v112
	v_log_f32_e32 v82, v82
	v_exp_f32_e32 v80, v80
	v_exp_f32_e32 v81, v81
	v_mul_f32_e32 v112, 0x3f317217, v82
	v_fma_f32 v112, v82, s95, -v112
	v_fmac_f32_e32 v112, 0x3377d1cf, v82
	v_fmac_f32_e32 v112, 0x3f317217, v82
	v_cmp_lt_f32_e64 s[46:47], |v82|, s62
	v_add_f32_e32 v80, 1.0, v80
	v_add_f32_e32 v81, 1.0, v81
	v_cndmask_b32_e64 v82, v82, v112, s[46:47]
	v_cndmask_b32_e32 v112, 0, v225, vcc
	v_sub_f32_e32 v112, v82, v112
	v_max_f32_e32 v82, 0xda24260, v83
	v_cmp_gt_f32_e32 vcc, s93, v82
	v_rcp_f32_e32 v80, v80
	v_rcp_f32_e32 v81, v81
	v_cndmask_b32_e64 v83, 0, 32, vcc
	v_ldexp_f32 v82, v82, v83
	v_log_f32_e32 v82, v82
	v_pk_mul_f32 v[80:81], v[80:81], v[116:117]
	v_mul_f32_e32 v83, 0x3f317217, v82
	v_fma_f32 v83, v82, s95, -v83
	v_fmac_f32_e32 v83, 0x3377d1cf, v82
	v_fmac_f32_e32 v83, 0x3f317217, v82
	v_cmp_lt_f32_e64 s[46:47], |v82|, s62
	s_nop 1
	v_cndmask_b32_e64 v82, v82, v83, s[46:47]
	v_cndmask_b32_e32 v83, 0, v225, vcc
	v_sub_f32_e32 v113, v82, v83
	v_pk_mul_f32 v[82:83], v[108:109], v[114:115]
	global_store_dwordx4 v[96:97], v[84:87], off
	global_store_dwordx4 v[96:97], v[110:113], off offset:16

.LBB0_432:
	s_andn2_b64 vcc, exec, s[36:37]
	s_cbranch_vccnz .LBB0_434
	v_mul_f32_e32 v80, 0xbfb8aa3b, v94
	v_exp_f32_e32 v80, v80
	v_mul_f32_e32 v105, 0xbfb8aa3b, v97
	v_exp_f32_e32 v105, v105
	v_mul_f32_e32 v109, 0xbfb8aa3b, v93
	v_add_f32_e32 v80, 1.0, v80
	v_rcp_f32_e32 v91, v80
	v_mul_f32_e32 v80, 0x3fb8aa3b, v94
	v_exp_f32_e32 v80, v80
	v_add_f32_e32 v105, 1.0, v105
	v_rcp_f32_e32 v108, v105
	v_exp_f32_e32 v109, v109
	v_add_f32_e32 v80, 1.0, v80
	v_rcp_f32_e32 v100, v80
	v_mul_f32_e32 v80, 0xbfb8aa3b, v95
	v_exp_f32_e32 v80, v80
	v_add_f32_e32 v109, 1.0, v109
	v_rcp_f32_e32 v111, v109
	v_mul_f32_e32 v105, 0x3fb8aa3b, v97
	v_add_f32_e32 v80, 1.0, v80
	v_rcp_f32_e32 v104, v80
	v_mul_f32_e32 v80, 0x3fb8aa3b, v95
	v_exp_f32_e32 v80, v80
	v_mul_f32_e32 v109, 0x3fb8aa3b, v93
	v_exp_f32_e32 v105, v105
	v_exp_f32_e32 v109, v109
	v_add_f32_e32 v80, 1.0, v80
	v_rcp_f32_e32 v101, v80
	global_load_dwordx4 v[80:83], v[148:149], off offset:16
	global_load_dwordx4 v[84:87], v[148:149], off
	v_add_f32_e32 v105, 1.0, v105
	v_add_f32_e32 v109, 1.0, v109
	v_rcp_f32_e32 v105, v105
	v_rcp_f32_e32 v109, v109
	s_waitcnt vmcnt(1)
	v_pk_add_f32 v[114:115], v[80:81], 1.0 op_sel_hi:[1,0] neg_lo:[1,0] neg_hi:[1,0]
	s_waitcnt vmcnt(0)
	v_pk_add_f32 v[102:103], v[84:85], 1.0 op_sel_hi:[1,0] neg_lo:[1,0] neg_hi:[1,0]
	v_pk_add_f32 v[106:107], v[86:87], 1.0 op_sel_hi:[1,0] neg_lo:[1,0] neg_hi:[1,0]
	v_fma_f32 v84, v91, v102, v84
	v_max_f32_e32 v84, 0xda24260, v84
	v_fma_f32 v85, v104, v103, v85
	v_max_f32_e32 v85, 0xda24260, v85
	v_log_f32_e32 v84, v84
	v_fmac_f32_e32 v87, v108, v107
	v_max_f32_e32 v87, 0xda24260, v87
	v_pk_add_f32 v[116:117], v[82:83], 1.0 op_sel_hi:[1,0] neg_lo:[1,0] neg_hi:[1,0]
	v_mul_f32_e32 v91, 0x3f317217, v84
	v_fma_f32 v91, v84, s95, -v91
	v_fmac_f32_e32 v91, 0x3377d1cf, v84
	v_fmac_f32_e32 v91, 0x3f317217, v84
	v_cmp_lt_f32_e64 s[46:47], |v84|, s62
	v_mul_f32_e32 v104, 0x3fb8aa3b, v96
	v_mul_f32_e32 v108, 0x3fb8aa3b, v92
	v_cndmask_b32_e64 v84, v84, v91, s[46:47]
	v_exp_f32_e32 v104, v104
	v_log_f32_e32 v85, v85
	v_exp_f32_e32 v108, v108
	v_add_f32_e32 v104, 1.0, v104
	v_rcp_f32_e32 v104, v104
	v_mul_f32_e32 v91, 0x3f317217, v85
	v_fma_f32 v91, v85, s95, -v91
	v_fmac_f32_e32 v91, 0x3377d1cf, v85
	v_fmac_f32_e32 v91, 0x3f317217, v85
	v_cmp_lt_f32_e64 s[46:47], |v85|, s62
	v_add_f32_e32 v108, 1.0, v108
	v_rcp_f32_e32 v108, v108
	v_cndmask_b32_e64 v85, v85, v91, s[46:47]
	v_mul_f32_e32 v91, 0xbfb8aa3b, v96
	v_exp_f32_e32 v91, v91
	v_pk_mul_f32 v[102:103], v[100:101], v[102:103]
	v_pk_mul_f32 v[100:101], v[104:105], v[106:107]
	v_lshl_add_u64 v[104:105], v[146:147], 0, v[88:89]
	v_add_f32_e32 v91, 1.0, v91
	v_rcp_f32_e32 v91, v91
	s_nop 0
	v_fma_f32 v86, v91, v106, v86
	v_max_f32_e32 v86, 0xda24260, v86
	s_nop 1
	v_log_f32_e32 v86, v86
	s_nop 0
	v_mul_f32_e32 v91, 0x3f317217, v86
	v_fma_f32 v91, v86, s95, -v91
	v_fmac_f32_e32 v91, 0x3377d1cf, v86
	v_fmac_f32_e32 v91, 0x3f317217, v86
	v_cmp_lt_f32_e64 s[46:47], |v86|, s62
	s_nop 1
	v_cndmask_b32_e64 v86, v86, v91, s[46:47]
	s_nop 0
	v_log_f32_e32 v87, v87
	s_nop 0
	v_mul_f32_e32 v91, 0x3f317217, v87
	v_fma_f32 v91, v87, s95, -v91
	v_fmac_f32_e32 v91, 0x3377d1cf, v87
	v_fmac_f32_e32 v91, 0x3f317217, v87
	v_cmp_lt_f32_e64 s[46:47], |v87|, s62
	s_nop 1
	v_cndmask_b32_e64 v87, v87, v91, s[46:47]
	v_mul_f32_e32 v91, 0xbfb8aa3b, v92
	v_exp_f32_e32 v91, v91
	s_nop 0
	v_add_f32_e32 v91, 1.0, v91
	v_rcp_f32_e32 v91, v91
	s_nop 0
	v_fma_f32 v80, v91, v114, v80
	v_max_f32_e32 v80, 0xda24260, v80
	v_cmp_gt_f32_e32 vcc, s93, v80
	s_nop 1
	v_cndmask_b32_e64 v91, 0, 32, vcc
	v_ldexp_f32 v80, v80, v91
	v_log_f32_e32 v80, v80
	s_nop 0
	v_mul_f32_e32 v91, 0x3f317217, v80
	v_fma_f32 v91, v80, s95, -v91
	v_fmac_f32_e32 v91, 0x3377d1cf, v80
	v_fmac_f32_e32 v91, 0x3f317217, v80
	v_cmp_lt_f32_e64 s[46:47], |v80|, s62
	s_nop 1
	v_cndmask_b32_e64 v80, v80, v91, s[46:47]
	v_cndmask_b32_e32 v91, 0, v225, vcc
	v_sub_f32_e32 v110, v80, v91
	v_fma_f32 v80, v111, v115, v81
	v_max_f32_e32 v80, 0xda24260, v80
	v_cmp_gt_f32_e32 vcc, s93, v80
	s_nop 1
	v_cndmask_b32_e64 v81, 0, 32, vcc
	v_ldexp_f32 v80, v80, v81
	v_log_f32_e32 v80, v80
	s_nop 0
	v_mul_f32_e32 v81, 0x3f317217, v80
	v_fma_f32 v81, v80, s95, -v81
	v_fmac_f32_e32 v81, 0x3377d1cf, v80
	v_fmac_f32_e32 v81, 0x3f317217, v80
	v_cmp_lt_f32_e64 s[46:47], |v80|, s62
	s_nop 1
	v_cndmask_b32_e64 v80, v80, v81, s[46:47]
	v_cndmask_b32_e32 v81, 0, v225, vcc
	v_sub_f32_e32 v111, v80, v81
	v_mul_f32_e32 v80, 0xbfb8aa3b, v98
	v_exp_f32_e32 v80, v80
	v_mul_f32_e32 v81, 0xbfb8aa3b, v99
	v_exp_f32_e32 v81, v81
	v_add_f32_e32 v80, 1.0, v80
	v_rcp_f32_e32 v91, v80
	v_add_f32_e32 v81, 1.0, v81
	v_rcp_f32_e32 v113, v81
	v_mul_f32_e32 v80, 0x3fb8aa3b, v98
	v_fma_f32 v82, v91, v116, v82
	v_max_f32_e32 v82, 0xda24260, v82
	v_cmp_gt_f32_e32 vcc, s93, v82
	v_fmac_f32_e32 v83, v113, v117
	v_mul_f32_e32 v81, 0x3fb8aa3b, v99
	v_cndmask_b32_e64 v91, 0, 32, vcc
	v_ldexp_f32 v82, v82, v91
	v_log_f32_e32 v82, v82
	v_exp_f32_e32 v80, v80
	v_exp_f32_e32 v81, v81
	v_mul_f32_e32 v91, 0x3f317217, v82
	v_fma_f32 v91, v82, s95, -v91
	v_fmac_f32_e32 v91, 0x3377d1cf, v82
	v_fmac_f32_e32 v91, 0x3f317217, v82
	v_cmp_lt_f32_e64 s[46:47], |v82|, s62
	v_add_f32_e32 v80, 1.0, v80
	v_add_f32_e32 v81, 1.0, v81
	v_cndmask_b32_e64 v82, v82, v91, s[46:47]
	v_cndmask_b32_e32 v91, 0, v225, vcc
	v_sub_f32_e32 v112, v82, v91
	v_max_f32_e32 v82, 0xda24260, v83
	v_cmp_gt_f32_e32 vcc, s93, v82
	v_rcp_f32_e32 v80, v80
	v_rcp_f32_e32 v81, v81
	v_cndmask_b32_e64 v83, 0, 32, vcc
	v_ldexp_f32 v82, v82, v83
	v_log_f32_e32 v82, v82
	v_pk_mul_f32 v[80:81], v[80:81], v[116:117]
	v_mul_f32_e32 v83, 0x3f317217, v82
	v_fma_f32 v83, v82, s95, -v83
	v_fmac_f32_e32 v83, 0x3377d1cf, v82
	v_fmac_f32_e32 v83, 0x3f317217, v82
	v_cmp_lt_f32_e64 s[46:47], |v82|, s62
	s_nop 1
	v_cndmask_b32_e64 v82, v82, v83, s[46:47]
	v_cndmask_b32_e32 v83, 0, v225, vcc
	v_sub_f32_e32 v113, v82, v83
	v_pk_mul_f32 v[82:83], v[108:109], v[114:115]
	global_store_dwordx4 v[104:105], v[84:87], off
	global_store_dwordx4 v[104:105], v[110:113], off offset:16

.LBB0_444:
	s_andn2_b64 vcc, exec, s[36:37]
	s_cbranch_vccnz .LBB0_446
	global_load_dwordx4 v[72:75], v[148:149], off offset:528
	global_load_dwordx4 v[76:79], v[148:149], off offset:512
	v_mul_f32_e32 v92, 0xbfb8aa3b, v84
	v_exp_f32_e32 v92, v92
	v_mul_f32_e32 v93, 0xbfb8aa3b, v85
	v_exp_f32_e32 v93, v93
	v_lshl_add_u64 v[88:89], v[150:151], 0, v[88:89]
	v_add_f32_e32 v92, 1.0, v92
	v_rcp_f32_e32 v96, v92
	v_add_f32_e32 v93, 1.0, v93
	v_rcp_f32_e32 v97, v93
	v_mul_f32_e32 v92, 0x3fb8aa3b, v84
	v_mul_f32_e32 v93, 0x3fb8aa3b, v85
	v_exp_f32_e32 v92, v92
	v_exp_f32_e32 v93, v93
	v_add_f32_e32 v92, 1.0, v92
	v_add_f32_e32 v93, 1.0, v93
	v_rcp_f32_e32 v92, v92
	v_rcp_f32_e32 v93, v93
	s_waitcnt vmcnt(1)
	v_pk_add_f32 v[106:107], v[72:73], 1.0 op_sel_hi:[1,0] neg_lo:[1,0] neg_hi:[1,0]
	s_waitcnt vmcnt(0)
	v_pk_add_f32 v[94:95], v[76:77], 1.0 op_sel_hi:[1,0] neg_lo:[1,0] neg_hi:[1,0]
	v_pk_add_f32 v[98:99], v[78:79], 1.0 op_sel_hi:[1,0] neg_lo:[1,0] neg_hi:[1,0]
	v_fma_f32 v76, v96, v94, v76
	v_max_f32_e32 v76, 0xda24260, v76
	v_fma_f32 v77, v97, v95, v77
	v_max_f32_e32 v77, 0xda24260, v77
	v_log_f32_e32 v76, v76
	v_mul_f32_e32 v97, 0xbfb8aa3b, v87
	v_exp_f32_e32 v97, v97
	v_pk_add_f32 v[108:109], v[74:75], 1.0 op_sel_hi:[1,0] neg_lo:[1,0] neg_hi:[1,0]
	v_mul_f32_e32 v96, 0x3f317217, v76
	v_fma_f32 v96, v76, s95, -v96
	v_fmac_f32_e32 v96, 0x3377d1cf, v76
	v_fmac_f32_e32 v96, 0x3f317217, v76
	v_cmp_lt_f32_e64 s[46:47], |v76|, s62
	v_add_f32_e32 v97, 1.0, v97
	v_rcp_f32_e32 v101, v97
	v_cndmask_b32_e64 v76, v76, v96, s[46:47]
	v_fmac_f32_e32 v79, v101, v99
	v_log_f32_e32 v77, v77
	v_max_f32_e32 v79, 0xda24260, v79
	v_mul_f32_e32 v101, 0xbfb8aa3b, v83
	v_exp_f32_e32 v101, v101
	v_mul_f32_e32 v96, 0x3f317217, v77
	v_fma_f32 v96, v77, s95, -v96
	v_fmac_f32_e32 v96, 0x3377d1cf, v77
	v_fmac_f32_e32 v96, 0x3f317217, v77
	v_cmp_lt_f32_e64 s[46:47], |v77|, s62
	v_add_f32_e32 v101, 1.0, v101
	v_rcp_f32_e32 v103, v101
	v_cndmask_b32_e64 v77, v77, v96, s[46:47]
	v_mul_f32_e32 v96, 0xbfb8aa3b, v86
	v_exp_f32_e32 v96, v96
	v_mul_f32_e32 v97, 0x3fb8aa3b, v87
	v_mul_f32_e32 v101, 0x3fb8aa3b, v83
	v_exp_f32_e32 v97, v97
	v_add_f32_e32 v96, 1.0, v96
	v_rcp_f32_e32 v100, v96
	v_mul_f32_e32 v96, 0x3fb8aa3b, v86
	v_exp_f32_e32 v96, v96
	v_exp_f32_e32 v101, v101
	v_fma_f32 v78, v100, v98, v78
	v_max_f32_e32 v78, 0xda24260, v78
	v_add_f32_e32 v96, 1.0, v96
	v_add_f32_e32 v97, 1.0, v97
	v_log_f32_e32 v78, v78
	v_add_f32_e32 v101, 1.0, v101
	v_rcp_f32_e32 v96, v96
	v_rcp_f32_e32 v97, v97
	v_mul_f32_e32 v100, 0x3f317217, v78
	v_fma_f32 v100, v78, s95, -v100
	v_fmac_f32_e32 v100, 0x3377d1cf, v78
	v_fmac_f32_e32 v100, 0x3f317217, v78
	v_cmp_lt_f32_e64 s[46:47], |v78|, s62
	v_rcp_f32_e32 v101, v101
	v_pk_mul_f32 v[94:95], v[92:93], v[94:95]
	v_cndmask_b32_e64 v78, v78, v100, s[46:47]
	v_pk_mul_f32 v[92:93], v[96:97], v[98:99]
	v_log_f32_e32 v79, v79
	s_nop 0
	v_mul_f32_e32 v100, 0x3f317217, v79
	v_fma_f32 v100, v79, s95, -v100
	v_fmac_f32_e32 v100, 0x3377d1cf, v79
	v_fmac_f32_e32 v100, 0x3f317217, v79
	v_cmp_lt_f32_e64 s[46:47], |v79|, s62
	s_nop 1
	v_cndmask_b32_e64 v79, v79, v100, s[46:47]
	v_mul_f32_e32 v100, 0xbfb8aa3b, v82
	v_exp_f32_e32 v100, v100
	s_nop 0
	v_add_f32_e32 v100, 1.0, v100
	v_rcp_f32_e32 v102, v100
	v_mul_f32_e32 v100, 0x3fb8aa3b, v82
	v_exp_f32_e32 v100, v100
	v_fma_f32 v72, v102, v106, v72
	v_max_f32_e32 v72, 0xda24260, v72
	v_cmp_gt_f32_e32 vcc, s93, v72
	v_add_f32_e32 v100, 1.0, v100
	v_rcp_f32_e32 v100, v100
	v_cndmask_b32_e64 v102, 0, 32, vcc
	v_ldexp_f32 v72, v72, v102
	v_log_f32_e32 v72, v72
	s_nop 0
	v_mul_f32_e32 v102, 0x3f317217, v72
	v_fma_f32 v102, v72, s95, -v102
	v_fmac_f32_e32 v102, 0x3377d1cf, v72
	v_fmac_f32_e32 v102, 0x3f317217, v72
	v_cmp_lt_f32_e64 s[46:47], |v72|, s62
	s_nop 1
	v_cndmask_b32_e64 v72, v72, v102, s[46:47]
	v_cndmask_b32_e32 v102, 0, v225, vcc
	v_sub_f32_e32 v102, v72, v102
	v_fma_f32 v72, v103, v107, v73
	v_max_f32_e32 v72, 0xda24260, v72
	v_cmp_gt_f32_e32 vcc, s93, v72
	s_nop 1
	v_cndmask_b32_e64 v73, 0, 32, vcc
	v_ldexp_f32 v72, v72, v73
	v_log_f32_e32 v72, v72
	s_nop 0
	v_mul_f32_e32 v73, 0x3f317217, v72
	v_fma_f32 v73, v72, s95, -v73
	v_fmac_f32_e32 v73, 0x3377d1cf, v72
	v_fmac_f32_e32 v73, 0x3f317217, v72
	v_cmp_lt_f32_e64 s[46:47], |v72|, s62
	s_nop 1
	v_cndmask_b32_e64 v72, v72, v73, s[46:47]
	v_cndmask_b32_e32 v73, 0, v225, vcc
	v_sub_f32_e32 v103, v72, v73
	v_mul_f32_e32 v72, 0xbfb8aa3b, v90
	v_exp_f32_e32 v72, v72
	v_mul_f32_e32 v73, 0xbfb8aa3b, v91
	v_exp_f32_e32 v73, v73
	v_add_f32_e32 v72, 1.0, v72
	v_rcp_f32_e32 v104, v72
	v_add_f32_e32 v73, 1.0, v73
	v_rcp_f32_e32 v105, v73
	v_mul_f32_e32 v72, 0x3fb8aa3b, v90
	v_fma_f32 v74, v104, v108, v74
	v_max_f32_e32 v74, 0xda24260, v74
	v_cmp_gt_f32_e32 vcc, s93, v74
	v_fmac_f32_e32 v75, v105, v109
	v_mul_f32_e32 v73, 0x3fb8aa3b, v91
	v_cndmask_b32_e64 v104, 0, 32, vcc
	v_ldexp_f32 v74, v74, v104
	v_log_f32_e32 v74, v74
	v_exp_f32_e32 v72, v72
	v_exp_f32_e32 v73, v73
	v_mul_f32_e32 v104, 0x3f317217, v74
	v_fma_f32 v104, v74, s95, -v104
	v_fmac_f32_e32 v104, 0x3377d1cf, v74
	v_fmac_f32_e32 v104, 0x3f317217, v74
	v_cmp_lt_f32_e64 s[46:47], |v74|, s62
	v_add_f32_e32 v72, 1.0, v72
	v_add_f32_e32 v73, 1.0, v73
	v_cndmask_b32_e64 v74, v74, v104, s[46:47]
	v_cndmask_b32_e32 v104, 0, v225, vcc
	v_sub_f32_e32 v104, v74, v104
	v_max_f32_e32 v74, 0xda24260, v75
	v_cmp_gt_f32_e32 vcc, s93, v74
	v_rcp_f32_e32 v72, v72
	v_rcp_f32_e32 v73, v73
	v_cndmask_b32_e64 v75, 0, 32, vcc
	v_ldexp_f32 v74, v74, v75
	v_log_f32_e32 v74, v74
	v_pk_mul_f32 v[72:73], v[72:73], v[108:109]
	v_mul_f32_e32 v75, 0x3f317217, v74
	v_fma_f32 v75, v74, s95, -v75
	v_fmac_f32_e32 v75, 0x3377d1cf, v74
	v_fmac_f32_e32 v75, 0x3f317217, v74
	v_cmp_lt_f32_e64 s[46:47], |v74|, s62
	s_nop 1
	v_cndmask_b32_e64 v74, v74, v75, s[46:47]
	v_cndmask_b32_e32 v75, 0, v225, vcc
	v_sub_f32_e32 v105, v74, v75
	v_pk_mul_f32 v[74:75], v[100:101], v[106:107]
	global_store_dwordx4 v[88:89], v[76:79], off
	global_store_dwordx4 v[88:89], v[102:105], off offset:16

.LBB0_456:
	s_andn2_b64 vcc, exec, s[36:37]
	s_cbranch_vccnz .LBB0_458
	v_mul_f32_e32 v72, 0xbfb8aa3b, v86
	v_exp_f32_e32 v72, v72
	v_mul_f32_e32 v97, 0xbfb8aa3b, v89
	v_exp_f32_e32 v97, v97
	v_mul_f32_e32 v101, 0xbfb8aa3b, v85
	v_add_f32_e32 v72, 1.0, v72
	v_rcp_f32_e32 v83, v72
	v_mul_f32_e32 v72, 0x3fb8aa3b, v86
	v_exp_f32_e32 v72, v72
	v_add_f32_e32 v97, 1.0, v97
	v_rcp_f32_e32 v100, v97
	v_exp_f32_e32 v101, v101
	v_add_f32_e32 v72, 1.0, v72
	v_rcp_f32_e32 v92, v72
	v_mul_f32_e32 v72, 0xbfb8aa3b, v87
	v_exp_f32_e32 v72, v72
	v_add_f32_e32 v101, 1.0, v101
	v_rcp_f32_e32 v103, v101
	v_mul_f32_e32 v97, 0x3fb8aa3b, v89
	v_add_f32_e32 v72, 1.0, v72
	v_rcp_f32_e32 v96, v72
	v_mul_f32_e32 v72, 0x3fb8aa3b, v87
	v_exp_f32_e32 v72, v72
	v_mul_f32_e32 v101, 0x3fb8aa3b, v85
	v_exp_f32_e32 v97, v97
	v_exp_f32_e32 v101, v101
	v_add_f32_e32 v72, 1.0, v72
	v_rcp_f32_e32 v93, v72
	global_load_dwordx4 v[72:75], v[148:149], off offset:16
	global_load_dwordx4 v[76:79], v[148:149], off
	v_add_f32_e32 v97, 1.0, v97
	v_add_f32_e32 v101, 1.0, v101
	v_rcp_f32_e32 v97, v97
	v_rcp_f32_e32 v101, v101
	s_waitcnt vmcnt(1)
	v_pk_add_f32 v[106:107], v[72:73], 1.0 op_sel_hi:[1,0] neg_lo:[1,0] neg_hi:[1,0]
	s_waitcnt vmcnt(0)
	v_pk_add_f32 v[94:95], v[76:77], 1.0 op_sel_hi:[1,0] neg_lo:[1,0] neg_hi:[1,0]
	v_pk_add_f32 v[98:99], v[78:79], 1.0 op_sel_hi:[1,0] neg_lo:[1,0] neg_hi:[1,0]
	v_fma_f32 v76, v83, v94, v76
	v_max_f32_e32 v76, 0xda24260, v76
	v_fma_f32 v77, v96, v95, v77
	v_max_f32_e32 v77, 0xda24260, v77
	v_log_f32_e32 v76, v76
	v_fmac_f32_e32 v79, v100, v99
	v_max_f32_e32 v79, 0xda24260, v79
	v_pk_add_f32 v[108:109], v[74:75], 1.0 op_sel_hi:[1,0] neg_lo:[1,0] neg_hi:[1,0]
	v_mul_f32_e32 v83, 0x3f317217, v76
	v_fma_f32 v83, v76, s95, -v83
	v_fmac_f32_e32 v83, 0x3377d1cf, v76
	v_fmac_f32_e32 v83, 0x3f317217, v76
	v_cmp_lt_f32_e64 s[46:47], |v76|, s62
	v_mul_f32_e32 v96, 0x3fb8aa3b, v88
	v_mul_f32_e32 v100, 0x3fb8aa3b, v84
	v_cndmask_b32_e64 v76, v76, v83, s[46:47]
	v_exp_f32_e32 v96, v96
	v_log_f32_e32 v77, v77
	v_exp_f32_e32 v100, v100
	v_add_f32_e32 v96, 1.0, v96
	v_rcp_f32_e32 v96, v96
	v_mul_f32_e32 v83, 0x3f317217, v77
	v_fma_f32 v83, v77, s95, -v83
	v_fmac_f32_e32 v83, 0x3377d1cf, v77
	v_fmac_f32_e32 v83, 0x3f317217, v77
	v_cmp_lt_f32_e64 s[46:47], |v77|, s62
	v_add_f32_e32 v100, 1.0, v100
	v_rcp_f32_e32 v100, v100
	v_cndmask_b32_e64 v77, v77, v83, s[46:47]
	v_mul_f32_e32 v83, 0xbfb8aa3b, v88
	v_exp_f32_e32 v83, v83
	v_pk_mul_f32 v[94:95], v[92:93], v[94:95]
	v_pk_mul_f32 v[92:93], v[96:97], v[98:99]
	v_lshl_add_u64 v[96:97], v[146:147], 0, v[80:81]
	v_add_f32_e32 v83, 1.0, v83
	v_rcp_f32_e32 v83, v83
	s_nop 0
	v_fma_f32 v78, v83, v98, v78
	v_max_f32_e32 v78, 0xda24260, v78
	s_nop 1
	v_log_f32_e32 v78, v78
	s_nop 0
	v_mul_f32_e32 v83, 0x3f317217, v78
	v_fma_f32 v83, v78, s95, -v83
	v_fmac_f32_e32 v83, 0x3377d1cf, v78
	v_fmac_f32_e32 v83, 0x3f317217, v78
	v_cmp_lt_f32_e64 s[46:47], |v78|, s62
	s_nop 1
	v_cndmask_b32_e64 v78, v78, v83, s[46:47]
	s_nop 0
	v_log_f32_e32 v79, v79
	s_nop 0
	v_mul_f32_e32 v83, 0x3f317217, v79
	v_fma_f32 v83, v79, s95, -v83
	v_fmac_f32_e32 v83, 0x3377d1cf, v79
	v_fmac_f32_e32 v83, 0x3f317217, v79
	v_cmp_lt_f32_e64 s[46:47], |v79|, s62
	s_nop 1
	v_cndmask_b32_e64 v79, v79, v83, s[46:47]
	v_mul_f32_e32 v83, 0xbfb8aa3b, v84
	v_exp_f32_e32 v83, v83
	s_nop 0
	v_add_f32_e32 v83, 1.0, v83
	v_rcp_f32_e32 v83, v83
	s_nop 0
	v_fma_f32 v72, v83, v106, v72
	v_max_f32_e32 v72, 0xda24260, v72
	v_cmp_gt_f32_e32 vcc, s93, v72
	s_nop 1
	v_cndmask_b32_e64 v83, 0, 32, vcc
	v_ldexp_f32 v72, v72, v83
	v_log_f32_e32 v72, v72
	s_nop 0
	v_mul_f32_e32 v83, 0x3f317217, v72
	v_fma_f32 v83, v72, s95, -v83
	v_fmac_f32_e32 v83, 0x3377d1cf, v72
	v_fmac_f32_e32 v83, 0x3f317217, v72
	v_cmp_lt_f32_e64 s[46:47], |v72|, s62
	s_nop 1
	v_cndmask_b32_e64 v72, v72, v83, s[46:47]
	v_cndmask_b32_e32 v83, 0, v225, vcc
	v_sub_f32_e32 v102, v72, v83
	v_fma_f32 v72, v103, v107, v73
	v_max_f32_e32 v72, 0xda24260, v72
	v_cmp_gt_f32_e32 vcc, s93, v72
	s_nop 1
	v_cndmask_b32_e64 v73, 0, 32, vcc
	v_ldexp_f32 v72, v72, v73
	v_log_f32_e32 v72, v72
	s_nop 0
	v_mul_f32_e32 v73, 0x3f317217, v72
	v_fma_f32 v73, v72, s95, -v73
	v_fmac_f32_e32 v73, 0x3377d1cf, v72
	v_fmac_f32_e32 v73, 0x3f317217, v72
	v_cmp_lt_f32_e64 s[46:47], |v72|, s62
	s_nop 1
	v_cndmask_b32_e64 v72, v72, v73, s[46:47]
	v_cndmask_b32_e32 v73, 0, v225, vcc
	v_sub_f32_e32 v103, v72, v73
	v_mul_f32_e32 v72, 0xbfb8aa3b, v90
	v_exp_f32_e32 v72, v72
	v_mul_f32_e32 v73, 0xbfb8aa3b, v91
	v_exp_f32_e32 v73, v73
	v_add_f32_e32 v72, 1.0, v72
	v_rcp_f32_e32 v83, v72
	v_add_f32_e32 v73, 1.0, v73
	v_rcp_f32_e32 v105, v73
	v_mul_f32_e32 v72, 0x3fb8aa3b, v90
	v_fma_f32 v74, v83, v108, v74
	v_max_f32_e32 v74, 0xda24260, v74
	v_cmp_gt_f32_e32 vcc, s93, v74
	v_fmac_f32_e32 v75, v105, v109
	v_mul_f32_e32 v73, 0x3fb8aa3b, v91
	v_cndmask_b32_e64 v83, 0, 32, vcc
	v_ldexp_f32 v74, v74, v83
	v_log_f32_e32 v74, v74
	v_exp_f32_e32 v72, v72
	v_exp_f32_e32 v73, v73
	v_mul_f32_e32 v83, 0x3f317217, v74
	v_fma_f32 v83, v74, s95, -v83
	v_fmac_f32_e32 v83, 0x3377d1cf, v74
	v_fmac_f32_e32 v83, 0x3f317217, v74
	v_cmp_lt_f32_e64 s[46:47], |v74|, s62
	v_add_f32_e32 v72, 1.0, v72
	v_add_f32_e32 v73, 1.0, v73
	v_cndmask_b32_e64 v74, v74, v83, s[46:47]
	v_cndmask_b32_e32 v83, 0, v225, vcc
	v_sub_f32_e32 v104, v74, v83
	v_max_f32_e32 v74, 0xda24260, v75
	v_cmp_gt_f32_e32 vcc, s93, v74
	v_rcp_f32_e32 v72, v72
	v_rcp_f32_e32 v73, v73
	v_cndmask_b32_e64 v75, 0, 32, vcc
	v_ldexp_f32 v74, v74, v75
	v_log_f32_e32 v74, v74
	v_pk_mul_f32 v[72:73], v[72:73], v[108:109]
	v_mul_f32_e32 v75, 0x3f317217, v74
	v_fma_f32 v75, v74, s95, -v75
	v_fmac_f32_e32 v75, 0x3377d1cf, v74
	v_fmac_f32_e32 v75, 0x3f317217, v74
	v_cmp_lt_f32_e64 s[46:47], |v74|, s62
	s_nop 1
	v_cndmask_b32_e64 v74, v74, v75, s[46:47]
	v_cndmask_b32_e32 v75, 0, v225, vcc
	v_sub_f32_e32 v105, v74, v75
	v_pk_mul_f32 v[74:75], v[100:101], v[106:107]
	global_store_dwordx4 v[96:97], v[76:79], off
	global_store_dwordx4 v[96:97], v[102:105], off offset:16

.LBB0_468:
	s_andn2_b64 vcc, exec, s[30:31]
	s_cbranch_vccnz .LBB0_470
	global_load_dwordx4 v[64:67], v[148:149], off offset:528
	global_load_dwordx4 v[68:71], v[148:149], off offset:512
	v_mul_f32_e32 v84, 0xbfb8aa3b, v76
	v_exp_f32_e32 v84, v84
	v_mul_f32_e32 v85, 0xbfb8aa3b, v77
	v_exp_f32_e32 v85, v85
	v_lshl_add_u64 v[80:81], v[150:151], 0, v[80:81]
	v_add_f32_e32 v84, 1.0, v84
	v_rcp_f32_e32 v88, v84
	v_add_f32_e32 v85, 1.0, v85
	v_rcp_f32_e32 v89, v85
	v_mul_f32_e32 v84, 0x3fb8aa3b, v76
	v_mul_f32_e32 v85, 0x3fb8aa3b, v77
	v_exp_f32_e32 v84, v84
	v_exp_f32_e32 v85, v85
	v_add_f32_e32 v84, 1.0, v84
	v_add_f32_e32 v85, 1.0, v85
	v_rcp_f32_e32 v84, v84
	v_rcp_f32_e32 v85, v85
	s_waitcnt vmcnt(1)
	v_pk_add_f32 v[98:99], v[64:65], 1.0 op_sel_hi:[1,0] neg_lo:[1,0] neg_hi:[1,0]
	s_waitcnt vmcnt(0)
	v_pk_add_f32 v[86:87], v[68:69], 1.0 op_sel_hi:[1,0] neg_lo:[1,0] neg_hi:[1,0]
	v_pk_add_f32 v[90:91], v[70:71], 1.0 op_sel_hi:[1,0] neg_lo:[1,0] neg_hi:[1,0]
	v_fma_f32 v68, v88, v86, v68
	v_max_f32_e32 v68, 0xda24260, v68
	v_fma_f32 v69, v89, v87, v69
	v_max_f32_e32 v69, 0xda24260, v69
	v_log_f32_e32 v68, v68
	v_mul_f32_e32 v89, 0xbfb8aa3b, v79
	v_exp_f32_e32 v89, v89
	v_pk_add_f32 v[100:101], v[66:67], 1.0 op_sel_hi:[1,0] neg_lo:[1,0] neg_hi:[1,0]
	v_mul_f32_e32 v88, 0x3f317217, v68
	v_fma_f32 v88, v68, s95, -v88
	v_fmac_f32_e32 v88, 0x3377d1cf, v68
	v_fmac_f32_e32 v88, 0x3f317217, v68
	v_cmp_lt_f32_e64 s[42:43], |v68|, s62
	v_add_f32_e32 v89, 1.0, v89
	v_rcp_f32_e32 v93, v89
	v_cndmask_b32_e64 v68, v68, v88, s[42:43]
	v_fmac_f32_e32 v71, v93, v91
	v_log_f32_e32 v69, v69
	v_max_f32_e32 v71, 0xda24260, v71
	v_mul_f32_e32 v93, 0xbfb8aa3b, v75
	v_exp_f32_e32 v93, v93
	v_mul_f32_e32 v88, 0x3f317217, v69
	v_fma_f32 v88, v69, s95, -v88
	v_fmac_f32_e32 v88, 0x3377d1cf, v69
	v_fmac_f32_e32 v88, 0x3f317217, v69
	v_cmp_lt_f32_e64 s[42:43], |v69|, s62
	v_add_f32_e32 v93, 1.0, v93
	v_rcp_f32_e32 v95, v93
	v_cndmask_b32_e64 v69, v69, v88, s[42:43]
	v_mul_f32_e32 v88, 0xbfb8aa3b, v78
	v_exp_f32_e32 v88, v88
	v_mul_f32_e32 v89, 0x3fb8aa3b, v79
	v_mul_f32_e32 v93, 0x3fb8aa3b, v75
	v_exp_f32_e32 v89, v89
	v_add_f32_e32 v88, 1.0, v88
	v_rcp_f32_e32 v92, v88
	v_mul_f32_e32 v88, 0x3fb8aa3b, v78
	v_exp_f32_e32 v88, v88
	v_exp_f32_e32 v93, v93
	v_fma_f32 v70, v92, v90, v70
	v_max_f32_e32 v70, 0xda24260, v70
	v_add_f32_e32 v88, 1.0, v88
	v_add_f32_e32 v89, 1.0, v89
	v_log_f32_e32 v70, v70
	v_add_f32_e32 v93, 1.0, v93
	v_rcp_f32_e32 v88, v88
	v_rcp_f32_e32 v89, v89
	v_mul_f32_e32 v92, 0x3f317217, v70
	v_fma_f32 v92, v70, s95, -v92
	v_fmac_f32_e32 v92, 0x3377d1cf, v70
	v_fmac_f32_e32 v92, 0x3f317217, v70
	v_cmp_lt_f32_e64 s[42:43], |v70|, s62
	v_rcp_f32_e32 v93, v93
	v_pk_mul_f32 v[86:87], v[84:85], v[86:87]
	v_cndmask_b32_e64 v70, v70, v92, s[42:43]
	v_pk_mul_f32 v[84:85], v[88:89], v[90:91]
	v_log_f32_e32 v71, v71
	s_nop 0
	v_mul_f32_e32 v92, 0x3f317217, v71
	v_fma_f32 v92, v71, s95, -v92
	v_fmac_f32_e32 v92, 0x3377d1cf, v71
	v_fmac_f32_e32 v92, 0x3f317217, v71
	v_cmp_lt_f32_e64 s[42:43], |v71|, s62
	s_nop 1
	v_cndmask_b32_e64 v71, v71, v92, s[42:43]
	v_mul_f32_e32 v92, 0xbfb8aa3b, v74
	v_exp_f32_e32 v92, v92
	s_nop 0
	v_add_f32_e32 v92, 1.0, v92
	v_rcp_f32_e32 v94, v92
	v_mul_f32_e32 v92, 0x3fb8aa3b, v74
	v_exp_f32_e32 v92, v92
	v_fma_f32 v64, v94, v98, v64
	v_max_f32_e32 v64, 0xda24260, v64
	v_cmp_gt_f32_e32 vcc, s93, v64
	v_add_f32_e32 v92, 1.0, v92
	v_rcp_f32_e32 v92, v92
	v_cndmask_b32_e64 v94, 0, 32, vcc
	v_ldexp_f32 v64, v64, v94
	v_log_f32_e32 v64, v64
	s_nop 0
	v_mul_f32_e32 v94, 0x3f317217, v64
	v_fma_f32 v94, v64, s95, -v94
	v_fmac_f32_e32 v94, 0x3377d1cf, v64
	v_fmac_f32_e32 v94, 0x3f317217, v64
	v_cmp_lt_f32_e64 s[42:43], |v64|, s62
	s_nop 1
	v_cndmask_b32_e64 v64, v64, v94, s[42:43]
	v_cndmask_b32_e32 v94, 0, v225, vcc
	v_sub_f32_e32 v94, v64, v94
	v_fma_f32 v64, v95, v99, v65
	v_max_f32_e32 v64, 0xda24260, v64
	v_cmp_gt_f32_e32 vcc, s93, v64
	s_nop 1
	v_cndmask_b32_e64 v65, 0, 32, vcc
	v_ldexp_f32 v64, v64, v65
	v_log_f32_e32 v64, v64
	s_nop 0
	v_mul_f32_e32 v65, 0x3f317217, v64
	v_fma_f32 v65, v64, s95, -v65
	v_fmac_f32_e32 v65, 0x3377d1cf, v64
	v_fmac_f32_e32 v65, 0x3f317217, v64
	v_cmp_lt_f32_e64 s[42:43], |v64|, s62
	s_nop 1
	v_cndmask_b32_e64 v64, v64, v65, s[42:43]
	v_cndmask_b32_e32 v65, 0, v225, vcc
	v_sub_f32_e32 v95, v64, v65
	v_mul_f32_e32 v64, 0xbfb8aa3b, v82
	v_exp_f32_e32 v64, v64
	v_mul_f32_e32 v65, 0xbfb8aa3b, v83
	v_exp_f32_e32 v65, v65
	v_add_f32_e32 v64, 1.0, v64
	v_rcp_f32_e32 v96, v64
	v_add_f32_e32 v65, 1.0, v65
	v_rcp_f32_e32 v97, v65
	v_mul_f32_e32 v64, 0x3fb8aa3b, v82
	v_fma_f32 v66, v96, v100, v66
	v_max_f32_e32 v66, 0xda24260, v66
	v_cmp_gt_f32_e32 vcc, s93, v66
	v_fmac_f32_e32 v67, v97, v101
	v_mul_f32_e32 v65, 0x3fb8aa3b, v83
	v_cndmask_b32_e64 v96, 0, 32, vcc
	v_ldexp_f32 v66, v66, v96
	v_log_f32_e32 v66, v66
	v_exp_f32_e32 v64, v64
	v_exp_f32_e32 v65, v65
	v_mul_f32_e32 v96, 0x3f317217, v66
	v_fma_f32 v96, v66, s95, -v96
	v_fmac_f32_e32 v96, 0x3377d1cf, v66
	v_fmac_f32_e32 v96, 0x3f317217, v66
	v_cmp_lt_f32_e64 s[42:43], |v66|, s62
	v_add_f32_e32 v64, 1.0, v64
	v_add_f32_e32 v65, 1.0, v65
	v_cndmask_b32_e64 v66, v66, v96, s[42:43]
	v_cndmask_b32_e32 v96, 0, v225, vcc
	v_sub_f32_e32 v96, v66, v96
	v_max_f32_e32 v66, 0xda24260, v67
	v_cmp_gt_f32_e32 vcc, s93, v66
	v_rcp_f32_e32 v64, v64
	v_rcp_f32_e32 v65, v65
	v_cndmask_b32_e64 v67, 0, 32, vcc
	v_ldexp_f32 v66, v66, v67
	v_log_f32_e32 v66, v66
	v_pk_mul_f32 v[64:65], v[64:65], v[100:101]
	v_mul_f32_e32 v67, 0x3f317217, v66
	v_fma_f32 v67, v66, s95, -v67
	v_fmac_f32_e32 v67, 0x3377d1cf, v66
	v_fmac_f32_e32 v67, 0x3f317217, v66
	v_cmp_lt_f32_e64 s[42:43], |v66|, s62
	s_nop 1
	v_cndmask_b32_e64 v66, v66, v67, s[42:43]
	v_cndmask_b32_e32 v67, 0, v225, vcc
	v_sub_f32_e32 v97, v66, v67
	v_pk_mul_f32 v[66:67], v[92:93], v[98:99]
	global_store_dwordx4 v[80:81], v[68:71], off
	global_store_dwordx4 v[80:81], v[94:97], off offset:16
